# v43 + in each GEMM K-loop memory segment the global_load_lds group is issued before the ds_read group
# baseline (speedup 1.0000x reference)
.LBB0_142:
	s_add_u32 s18, s16, 0xfffc0080
	s_addc_u32 s19, s17, -1
	s_add_i32 s28, 0, 0x10000
	s_cmp_eq_u32 s88, 12
	s_cselect_b32 s53, s47, s19
	s_cselect_b32 s52, s78, s18
	s_cselect_b32 s19, s15, s85
	s_cselect_b32 s18, s79, s83
	s_add_i32 s29, 0, 0x14000
	v_lshl_add_u64 v[140:141], s[16:17], 0, v[136:137]
	s_add_i32 m0, s54, 0xc000
	s_nop 0
	global_load_lds_dwordx4 v[140:141], off
	v_lshl_add_u64 v[140:141], s[16:17], 0, v[138:139]
	s_add_i32 m0, s54, 0xe000
	s_nop 0
	global_load_lds_dwordx4 v[140:141], off
	v_add_u32_e32 v140, s28, v143
	ds_read_b128 v[146:149], v140
	ds_read_b128 v[150:153], v140 offset:1024
	ds_read_b128 v[154:157], v140 offset:2048
	ds_read_b128 v[158:161], v140 offset:3072
	v_add_u32_e32 v140, s29, v143
	ds_read_b128 v[162:165], v140
	ds_read_b128 v[166:169], v140 offset:1024
	ds_read_b128 v[174:177], v140 offset:2048
	ds_read_b128 v[178:181], v140 offset:3072
	ds_read_b128 v[182:185], v145
	ds_read_b128 v[186:189], v145 offset:1024
	ds_read_b128 v[190:193], v145 offset:2048
	ds_read_b128 v[194:197], v145 offset:3072
	ds_read_b128 v[198:201], v145 offset:4096
	ds_read_b128 v[202:205], v145 offset:5120
	ds_read_b128 v[236:239], v145 offset:6144
	ds_read_b128 v[240:243], v145 offset:7168
	s_waitcnt vmcnt(8)
	s_waitcnt lgkmcnt(0)
	s_barrier
	s_waitcnt lgkmcnt(0)
	v_mfma_f32_16x16x32_bf16 v[126:129], v[146:149], v[182:185], v[126:129]
	v_mfma_f32_16x16x32_bf16 v[118:121], v[154:157], v[182:185], v[118:121]
	v_mfma_f32_16x16x32_bf16 v[110:113], v[146:149], v[190:193], v[110:113]
	v_mfma_f32_16x16x32_bf16 v[102:105], v[154:157], v[190:193], v[102:105]
	v_mfma_f32_16x16x32_bf16 v[94:97], v[146:149], v[198:201], v[94:97]
	v_mfma_f32_16x16x32_bf16 v[86:89], v[154:157], v[198:201], v[86:89]
	v_mfma_f32_16x16x32_bf16 v[78:81], v[146:149], v[236:239], v[78:81]
	v_mfma_f32_16x16x32_bf16 v[70:73], v[154:157], v[236:239], v[70:73]
	v_mfma_f32_16x16x32_bf16 v[126:129], v[150:153], v[186:189], v[126:129]
	v_mfma_f32_16x16x32_bf16 v[118:121], v[158:161], v[186:189], v[118:121]
	v_mfma_f32_16x16x32_bf16 v[110:113], v[150:153], v[194:197], v[110:113]
	v_mfma_f32_16x16x32_bf16 v[102:105], v[158:161], v[194:197], v[102:105]
	v_mfma_f32_16x16x32_bf16 v[94:97], v[150:153], v[202:205], v[94:97]
	v_mfma_f32_16x16x32_bf16 v[86:89], v[158:161], v[202:205], v[86:89]
	v_mfma_f32_16x16x32_bf16 v[78:81], v[150:153], v[240:243], v[78:81]
	v_mfma_f32_16x16x32_bf16 v[70:73], v[158:161], v[240:243], v[70:73]
	v_mfma_f32_16x16x32_bf16 v[122:125], v[162:165], v[182:185], v[122:125]
	v_mfma_f32_16x16x32_bf16 v[114:117], v[174:177], v[182:185], v[114:117]
	v_mfma_f32_16x16x32_bf16 v[106:109], v[162:165], v[190:193], v[106:109]
	v_mfma_f32_16x16x32_bf16 v[98:101], v[174:177], v[190:193], v[98:101]
	v_mfma_f32_16x16x32_bf16 v[90:93], v[162:165], v[198:201], v[90:93]
	v_mfma_f32_16x16x32_bf16 v[82:85], v[174:177], v[198:201], v[82:85]
	v_mfma_f32_16x16x32_bf16 v[74:77], v[162:165], v[236:239], v[74:77]
	v_mfma_f32_16x16x32_bf16 v[66:69], v[174:177], v[236:239], v[66:69]
	v_mfma_f32_16x16x32_bf16 v[122:125], v[166:169], v[186:189], v[122:125]
	v_mfma_f32_16x16x32_bf16 v[114:117], v[178:181], v[186:189], v[114:117]
	v_mfma_f32_16x16x32_bf16 v[106:109], v[166:169], v[194:197], v[106:109]
	v_mfma_f32_16x16x32_bf16 v[98:101], v[178:181], v[194:197], v[98:101]
	v_mfma_f32_16x16x32_bf16 v[90:93], v[166:169], v[202:205], v[90:93]
	v_mfma_f32_16x16x32_bf16 v[82:85], v[178:181], v[202:205], v[82:85]
	v_mfma_f32_16x16x32_bf16 v[74:77], v[166:169], v[240:243], v[74:77]
	v_mfma_f32_16x16x32_bf16 v[66:69], v[178:181], v[240:243], v[66:69]
	s_barrier
	s_add_i32 s28, s28, s41
	v_lshl_add_u64 v[140:141], s[18:19], 0, v[0:1]
	s_mov_b32 m0, s28
	s_nop 0
	global_load_lds_dwordx4 v[140:141], off
	s_add_i32 m0, s28, 0x2000
	s_add_u32 s36, s18, 0x40000
	v_lshl_add_u64 v[206:207], s[18:19], 0, v[130:131]
	s_addc_u32 s37, s19, 0
	s_add_i32 s28, s29, s41
	global_load_lds_dwordx4 v[206:207], off
	v_lshl_add_u64 v[228:229], s[36:37], 0, v[0:1]
	s_mov_b32 m0, s28
	v_lshl_add_u64 v[244:245], s[52:53], 0, v[132:133]
	global_load_lds_dwordx4 v[228:229], off
	v_lshl_add_u64 v[228:229], s[36:37], 0, v[130:131]
	s_add_i32 m0, s28, 0x2000
	s_nop 0
	global_load_lds_dwordx4 v[228:229], off
	v_lshl_add_u64 v[228:229], s[52:53], 0, v[134:135]
	s_mov_b32 m0, s54
	s_nop 0
	global_load_lds_dwordx4 v[228:229], off
	s_mov_b32 m0, s55
	s_nop 0
	global_load_lds_dwordx4 v[244:245], off
	ds_read_b128 v[182:185], v145 offset:16384
	ds_read_b128 v[186:189], v145 offset:17408
	ds_read_b128 v[190:193], v145 offset:18432
	ds_read_b128 v[194:197], v145 offset:19456
	ds_read_b128 v[198:201], v145 offset:20480
	ds_read_b128 v[202:205], v145 offset:21504
	ds_read_b128 v[236:239], v145 offset:22528
	ds_read_b128 v[240:243], v145 offset:23552
	s_waitcnt vmcnt(8)
	s_waitcnt lgkmcnt(0)
	s_barrier
	s_waitcnt lgkmcnt(0)
	v_mfma_f32_16x16x32_bf16 v[62:65], v[146:149], v[182:185], v[62:65]
	v_mfma_f32_16x16x32_bf16 v[54:57], v[154:157], v[182:185], v[54:57]
	v_mfma_f32_16x16x32_bf16 v[46:49], v[146:149], v[190:193], v[46:49]
	v_mfma_f32_16x16x32_bf16 v[38:41], v[154:157], v[190:193], v[38:41]
	v_mfma_f32_16x16x32_bf16 v[30:33], v[146:149], v[198:201], v[30:33]
	v_mfma_f32_16x16x32_bf16 v[22:25], v[154:157], v[198:201], v[22:25]
	v_mfma_f32_16x16x32_bf16 v[14:17], v[146:149], v[236:239], v[14:17]
	v_mfma_f32_16x16x32_bf16 v[6:9], v[154:157], v[236:239], v[6:9]
	v_mfma_f32_16x16x32_bf16 v[62:65], v[150:153], v[186:189], v[62:65]
	v_mfma_f32_16x16x32_bf16 v[54:57], v[158:161], v[186:189], v[54:57]
	v_mfma_f32_16x16x32_bf16 v[46:49], v[150:153], v[194:197], v[46:49]
	v_mfma_f32_16x16x32_bf16 v[38:41], v[158:161], v[194:197], v[38:41]
	v_mfma_f32_16x16x32_bf16 v[30:33], v[150:153], v[202:205], v[30:33]
	v_mfma_f32_16x16x32_bf16 v[22:25], v[158:161], v[202:205], v[22:25]
	v_mfma_f32_16x16x32_bf16 v[14:17], v[150:153], v[240:243], v[14:17]
	v_mfma_f32_16x16x32_bf16 v[6:9], v[158:161], v[240:243], v[6:9]
	v_mfma_f32_16x16x32_bf16 v[58:61], v[162:165], v[182:185], v[58:61]
	v_mfma_f32_16x16x32_bf16 v[50:53], v[174:177], v[182:185], v[50:53]
	v_mfma_f32_16x16x32_bf16 v[42:45], v[162:165], v[190:193], v[42:45]
	v_mfma_f32_16x16x32_bf16 v[34:37], v[174:177], v[190:193], v[34:37]
	v_mfma_f32_16x16x32_bf16 v[26:29], v[162:165], v[198:201], v[26:29]
	v_mfma_f32_16x16x32_bf16 v[18:21], v[174:177], v[198:201], v[18:21]
	v_mfma_f32_16x16x32_bf16 v[10:13], v[162:165], v[236:239], v[10:13]
	v_mfma_f32_16x16x32_bf16 v[2:5], v[174:177], v[236:239], v[2:5]
	v_mfma_f32_16x16x32_bf16 v[58:61], v[166:169], v[186:189], v[58:61]
	v_mfma_f32_16x16x32_bf16 v[50:53], v[178:181], v[186:189], v[50:53]
	v_mfma_f32_16x16x32_bf16 v[42:45], v[166:169], v[194:197], v[42:45]
	v_mfma_f32_16x16x32_bf16 v[34:37], v[178:181], v[194:197], v[34:37]
	v_mfma_f32_16x16x32_bf16 v[26:29], v[166:169], v[202:205], v[26:29]
	v_mfma_f32_16x16x32_bf16 v[18:21], v[178:181], v[202:205], v[18:21]
	v_mfma_f32_16x16x32_bf16 v[10:13], v[166:169], v[240:243], v[10:13]
	v_mfma_f32_16x16x32_bf16 v[2:5], v[178:181], v[240:243], v[2:5]
	s_barrier
	s_add_i32 s28, 0, 0x18000
	s_add_i32 s29, 0, 0x1c000
	s_add_u32 s36, s52, 0x40000
	s_addc_u32 s37, s53, 0
	s_mov_b32 m0, s70
	v_lshl_add_u64 v[246:247], s[36:37], 0, v[134:135]
	global_load_lds_dwordx4 v[246:247], off
	v_lshl_add_u64 v[246:247], s[36:37], 0, v[132:133]
	s_mov_b32 m0, s71
	s_nop 0
	global_load_lds_dwordx4 v[246:247], off
	v_add_u32_e32 v158, s28, v143
	v_add_u32_e32 v178, s29, v143
	ds_read_b128 v[146:149], v158
	ds_read_b128 v[150:153], v158 offset:1024
	ds_read_b128 v[154:157], v158 offset:2048
	ds_read_b128 v[158:161], v158 offset:3072
	ds_read_b128 v[162:165], v178
	ds_read_b128 v[166:169], v178 offset:1024
	ds_read_b128 v[174:177], v178 offset:2048
	ds_read_b128 v[178:181], v178 offset:3072
	ds_read_b128 v[182:185], v145 offset:32768
	ds_read_b128 v[186:189], v145 offset:33792
	ds_read_b128 v[190:193], v145 offset:34816
	ds_read_b128 v[194:197], v145 offset:35840
	ds_read_b128 v[198:201], v145 offset:36864
	ds_read_b128 v[202:205], v145 offset:37888
	ds_read_b128 v[236:239], v145 offset:38912
	ds_read_b128 v[240:243], v145 offset:39936
	s_waitcnt vmcnt(8)
	s_waitcnt lgkmcnt(0)
	s_barrier
	s_waitcnt lgkmcnt(0)
	v_mfma_f32_16x16x32_bf16 v[126:129], v[146:149], v[182:185], v[126:129]
	v_mfma_f32_16x16x32_bf16 v[118:121], v[154:157], v[182:185], v[118:121]
	v_mfma_f32_16x16x32_bf16 v[110:113], v[146:149], v[190:193], v[110:113]
	v_mfma_f32_16x16x32_bf16 v[102:105], v[154:157], v[190:193], v[102:105]
	v_mfma_f32_16x16x32_bf16 v[94:97], v[146:149], v[198:201], v[94:97]
	v_mfma_f32_16x16x32_bf16 v[86:89], v[154:157], v[198:201], v[86:89]
	v_mfma_f32_16x16x32_bf16 v[78:81], v[146:149], v[236:239], v[78:81]
	v_mfma_f32_16x16x32_bf16 v[70:73], v[154:157], v[236:239], v[70:73]
	v_mfma_f32_16x16x32_bf16 v[126:129], v[150:153], v[186:189], v[126:129]
	v_mfma_f32_16x16x32_bf16 v[118:121], v[158:161], v[186:189], v[118:121]
	v_mfma_f32_16x16x32_bf16 v[110:113], v[150:153], v[194:197], v[110:113]
	v_mfma_f32_16x16x32_bf16 v[102:105], v[158:161], v[194:197], v[102:105]
	v_mfma_f32_16x16x32_bf16 v[94:97], v[150:153], v[202:205], v[94:97]
	v_mfma_f32_16x16x32_bf16 v[86:89], v[158:161], v[202:205], v[86:89]
	v_mfma_f32_16x16x32_bf16 v[78:81], v[150:153], v[240:243], v[78:81]
	v_mfma_f32_16x16x32_bf16 v[70:73], v[158:161], v[240:243], v[70:73]
	v_mfma_f32_16x16x32_bf16 v[122:125], v[162:165], v[182:185], v[122:125]
	v_mfma_f32_16x16x32_bf16 v[114:117], v[174:177], v[182:185], v[114:117]
	v_mfma_f32_16x16x32_bf16 v[106:109], v[162:165], v[190:193], v[106:109]
	v_mfma_f32_16x16x32_bf16 v[98:101], v[174:177], v[190:193], v[98:101]
	v_mfma_f32_16x16x32_bf16 v[90:93], v[162:165], v[198:201], v[90:93]
	v_mfma_f32_16x16x32_bf16 v[82:85], v[174:177], v[198:201], v[82:85]
	v_mfma_f32_16x16x32_bf16 v[74:77], v[162:165], v[236:239], v[74:77]
	v_mfma_f32_16x16x32_bf16 v[66:69], v[174:177], v[236:239], v[66:69]
	v_mfma_f32_16x16x32_bf16 v[122:125], v[166:169], v[186:189], v[122:125]
	v_mfma_f32_16x16x32_bf16 v[114:117], v[178:181], v[186:189], v[114:117]
	v_mfma_f32_16x16x32_bf16 v[106:109], v[166:169], v[194:197], v[106:109]
	v_mfma_f32_16x16x32_bf16 v[98:101], v[178:181], v[194:197], v[98:101]
	v_mfma_f32_16x16x32_bf16 v[90:93], v[166:169], v[202:205], v[90:93]
	v_mfma_f32_16x16x32_bf16 v[82:85], v[178:181], v[202:205], v[82:85]
	v_mfma_f32_16x16x32_bf16 v[74:77], v[166:169], v[240:243], v[74:77]
	v_mfma_f32_16x16x32_bf16 v[66:69], v[178:181], v[240:243], v[66:69]
	s_barrier
	s_add_i32 s28, s28, s41
	v_lshl_add_u64 v[140:141], v[140:141], 0, s[4:5]
	s_mov_b32 m0, s28
	s_nop 0
	global_load_lds_dwordx4 v[140:141], off
	s_add_i32 m0, s28, 0x2000
	s_add_u32 s18, s18, 0x40080
	v_lshl_add_u64 v[140:141], v[206:207], 0, s[4:5]
	s_addc_u32 s19, s19, 0
	s_add_i32 s28, s29, s41
	global_load_lds_dwordx4 v[140:141], off
	v_lshl_add_u64 v[140:141], s[18:19], 0, v[0:1]
	s_mov_b32 m0, s28
	s_nop 0
	global_load_lds_dwordx4 v[140:141], off
	v_lshl_add_u64 v[140:141], s[18:19], 0, v[130:131]
	s_add_i32 m0, s28, 0x2000
	s_nop 0
	global_load_lds_dwordx4 v[140:141], off
	v_lshl_add_u64 v[140:141], v[228:229], 0, s[4:5]
	s_mov_b32 m0, s74
	s_nop 0
	global_load_lds_dwordx4 v[140:141], off
	v_lshl_add_u64 v[140:141], v[244:245], 0, s[4:5]
	s_mov_b32 m0, s75
	s_nop 0
	global_load_lds_dwordx4 v[140:141], off
	ds_read_b128 v[182:185], v145 offset:49152
	ds_read_b128 v[186:189], v145 offset:50176
	ds_read_b128 v[190:193], v145 offset:51200
	ds_read_b128 v[194:197], v145 offset:52224
	ds_read_b128 v[198:201], v145 offset:53248
	ds_read_b128 v[202:205], v145 offset:54272
	ds_read_b128 v[236:239], v145 offset:55296
	ds_read_b128 v[240:243], v145 offset:56320
	s_waitcnt vmcnt(8)
	s_waitcnt lgkmcnt(0)
	s_barrier
	s_waitcnt lgkmcnt(0)
	v_mfma_f32_16x16x32_bf16 v[62:65], v[146:149], v[182:185], v[62:65]
	v_mfma_f32_16x16x32_bf16 v[54:57], v[154:157], v[182:185], v[54:57]
	v_mfma_f32_16x16x32_bf16 v[46:49], v[146:149], v[190:193], v[46:49]
	v_mfma_f32_16x16x32_bf16 v[38:41], v[154:157], v[190:193], v[38:41]
	v_mfma_f32_16x16x32_bf16 v[30:33], v[146:149], v[198:201], v[30:33]
	v_mfma_f32_16x16x32_bf16 v[22:25], v[154:157], v[198:201], v[22:25]
	v_mfma_f32_16x16x32_bf16 v[14:17], v[146:149], v[236:239], v[14:17]
	v_mfma_f32_16x16x32_bf16 v[6:9], v[154:157], v[236:239], v[6:9]
	v_mfma_f32_16x16x32_bf16 v[62:65], v[150:153], v[186:189], v[62:65]
	v_mfma_f32_16x16x32_bf16 v[54:57], v[158:161], v[186:189], v[54:57]
	v_mfma_f32_16x16x32_bf16 v[46:49], v[150:153], v[194:197], v[46:49]
	v_mfma_f32_16x16x32_bf16 v[38:41], v[158:161], v[194:197], v[38:41]
	v_mfma_f32_16x16x32_bf16 v[30:33], v[150:153], v[202:205], v[30:33]
	v_mfma_f32_16x16x32_bf16 v[22:25], v[158:161], v[202:205], v[22:25]
	v_mfma_f32_16x16x32_bf16 v[14:17], v[150:153], v[240:243], v[14:17]
	v_mfma_f32_16x16x32_bf16 v[6:9], v[158:161], v[240:243], v[6:9]
	v_mfma_f32_16x16x32_bf16 v[58:61], v[162:165], v[182:185], v[58:61]
	v_mfma_f32_16x16x32_bf16 v[50:53], v[174:177], v[182:185], v[50:53]
	v_mfma_f32_16x16x32_bf16 v[42:45], v[162:165], v[190:193], v[42:45]
	v_mfma_f32_16x16x32_bf16 v[34:37], v[174:177], v[190:193], v[34:37]
	v_mfma_f32_16x16x32_bf16 v[26:29], v[162:165], v[198:201], v[26:29]
	v_mfma_f32_16x16x32_bf16 v[18:21], v[174:177], v[198:201], v[18:21]
	v_mfma_f32_16x16x32_bf16 v[10:13], v[162:165], v[236:239], v[10:13]
	v_mfma_f32_16x16x32_bf16 v[2:5], v[174:177], v[236:239], v[2:5]
	v_mfma_f32_16x16x32_bf16 v[58:61], v[166:169], v[186:189], v[58:61]
	v_mfma_f32_16x16x32_bf16 v[50:53], v[178:181], v[186:189], v[50:53]
	v_mfma_f32_16x16x32_bf16 v[42:45], v[166:169], v[194:197], v[42:45]
	v_mfma_f32_16x16x32_bf16 v[34:37], v[178:181], v[194:197], v[34:37]
	v_mfma_f32_16x16x32_bf16 v[26:29], v[166:169], v[202:205], v[26:29]
	v_mfma_f32_16x16x32_bf16 v[18:21], v[178:181], v[202:205], v[18:21]
	v_mfma_f32_16x16x32_bf16 v[10:13], v[166:169], v[240:243], v[10:13]
	v_mfma_f32_16x16x32_bf16 v[2:5], v[178:181], v[240:243], v[2:5]
	s_barrier
	s_add_i32 s88, s88, 2
	s_add_u32 s16, s16, 0x100
	s_addc_u32 s17, s17, 0
	s_add_u32 s83, s83, 0x100
	s_addc_u32 s85, s85, 0
	s_cmp_gt_u32 s88, 13
	s_cbranch_scc0 .LBB0_142
	s_and_b64 vcc, exec, s[12:13]
	s_cbranch_vccz .LBB0_145
	s_barrier

.LBB0_194:
	s_add_i32 vcc_lo, s12, 2
	s_add_u32 s36, s10, 0x80
	s_addc_u32 s13, s11, 0
	s_add_i32 vcc_hi, 0, 0x10000
	s_cmp_eq_u32 s94, s12
	s_cselect_b32 s13, s45, s13
	s_cselect_b32 s12, s44, s36
	s_cselect_b32 s37, s79, s15
	s_cselect_b32 s36, s78, s14
	s_add_i32 s8, 0, 0x14000
	v_lshl_add_u64 v[240:241], s[10:11], 0, v[180:181]
	s_add_i32 m0, s18, 0xc000
	s_nop 0
	global_load_lds_dwordx4 v[240:241], off
	v_lshl_add_u64 v[240:241], s[10:11], 0, v[182:183]
	s_add_i32 m0, s18, 0xe000
	s_nop 0
	global_load_lds_dwordx4 v[240:241], off
	v_add_u32_e32 v126, vcc_hi, v197
	v_add_u32_e32 v158, s8, v197
	ds_read_b128 v[114:117], v126
	ds_read_b128 v[118:121], v126 offset:1024
	ds_read_b128 v[122:125], v126 offset:2048
	ds_read_b128 v[126:129], v126 offset:3072
	ds_read_b128 v[146:149], v158
	ds_read_b128 v[150:153], v158 offset:1024
	ds_read_b128 v[154:157], v158 offset:2048
	ds_read_b128 v[158:161], v158 offset:3072
	ds_read_b128 v[162:165], v199
	ds_read_b128 v[166:169], v199 offset:1024
	ds_read_b128 v[184:187], v199 offset:2048
	ds_read_b128 v[188:191], v199 offset:3072
	ds_read_b128 v[192:195], v199 offset:4096
	ds_read_b128 v[200:203], v199 offset:5120
	ds_read_b128 v[204:207], v199 offset:6144
	ds_read_b128 v[236:239], v199 offset:7168
	s_waitcnt vmcnt(8)
	s_waitcnt lgkmcnt(0)
	s_barrier
	s_waitcnt lgkmcnt(0)
	v_mfma_f32_16x16x32_bf16 v[142:145], v[114:117], v[162:165], v[142:145]
	v_mfma_f32_16x16x32_bf16 v[138:141], v[122:125], v[162:165], v[138:141]
	v_mfma_f32_16x16x32_bf16 v[110:113], v[114:117], v[184:187], v[110:113]
	v_mfma_f32_16x16x32_bf16 v[106:109], v[122:125], v[184:187], v[106:109]
	v_mfma_f32_16x16x32_bf16 v[94:97], v[114:117], v[192:195], v[94:97]
	v_mfma_f32_16x16x32_bf16 v[90:93], v[122:125], v[192:195], v[90:93]
	v_mfma_f32_16x16x32_bf16 v[78:81], v[114:117], v[204:207], v[78:81]
	v_mfma_f32_16x16x32_bf16 v[74:77], v[122:125], v[204:207], v[74:77]
	v_mfma_f32_16x16x32_bf16 v[142:145], v[118:121], v[166:169], v[142:145]
	v_mfma_f32_16x16x32_bf16 v[138:141], v[126:129], v[166:169], v[138:141]
	v_mfma_f32_16x16x32_bf16 v[110:113], v[118:121], v[188:191], v[110:113]
	v_mfma_f32_16x16x32_bf16 v[106:109], v[126:129], v[188:191], v[106:109]
	v_mfma_f32_16x16x32_bf16 v[94:97], v[118:121], v[200:203], v[94:97]
	v_mfma_f32_16x16x32_bf16 v[90:93], v[126:129], v[200:203], v[90:93]
	v_mfma_f32_16x16x32_bf16 v[78:81], v[118:121], v[236:239], v[78:81]
	v_mfma_f32_16x16x32_bf16 v[74:77], v[126:129], v[236:239], v[74:77]
	v_mfma_f32_16x16x32_bf16 v[134:137], v[146:149], v[162:165], v[134:137]
	v_mfma_f32_16x16x32_bf16 v[130:133], v[154:157], v[162:165], v[130:133]
	v_mfma_f32_16x16x32_bf16 v[102:105], v[146:149], v[184:187], v[102:105]
	v_mfma_f32_16x16x32_bf16 v[98:101], v[154:157], v[184:187], v[98:101]
	v_mfma_f32_16x16x32_bf16 v[86:89], v[146:149], v[192:195], v[86:89]
	v_mfma_f32_16x16x32_bf16 v[82:85], v[154:157], v[192:195], v[82:85]
	v_mfma_f32_16x16x32_bf16 v[70:73], v[146:149], v[204:207], v[70:73]
	v_mfma_f32_16x16x32_bf16 v[66:69], v[154:157], v[204:207], v[66:69]
	v_mfma_f32_16x16x32_bf16 v[134:137], v[150:153], v[166:169], v[134:137]
	v_mfma_f32_16x16x32_bf16 v[130:133], v[158:161], v[166:169], v[130:133]
	v_mfma_f32_16x16x32_bf16 v[102:105], v[150:153], v[188:191], v[102:105]
	v_mfma_f32_16x16x32_bf16 v[98:101], v[158:161], v[188:191], v[98:101]
	v_mfma_f32_16x16x32_bf16 v[86:89], v[150:153], v[200:203], v[86:89]
	v_mfma_f32_16x16x32_bf16 v[82:85], v[158:161], v[200:203], v[82:85]
	v_mfma_f32_16x16x32_bf16 v[70:73], v[150:153], v[236:239], v[70:73]
	v_mfma_f32_16x16x32_bf16 v[66:69], v[158:161], v[236:239], v[66:69]
	s_barrier
	s_add_i32 s9, vcc_hi, s17
	v_lshl_add_u64 v[240:241], s[36:37], 0, v[0:1]
	s_mov_b32 m0, s9
	s_nop 0
	global_load_lds_dwordx4 v[240:241], off
	s_add_i32 m0, s9, 0x2000
	v_lshl_add_u64 v[242:243], s[36:37], 0, v[174:175]
	s_add_u32 s36, s36, s20
	s_addc_u32 s37, s37, 0
	s_add_i32 s8, s8, s17
	global_load_lds_dwordx4 v[242:243], off
	v_lshl_add_u64 v[244:245], s[36:37], 0, v[0:1]
	s_mov_b32 m0, s8
	v_lshl_add_u64 v[246:247], s[36:37], 0, v[174:175]
	global_load_lds_dwordx4 v[244:245], off
	s_add_i32 m0, s8, 0x2000
	v_lshl_add_u64 v[248:249], s[12:13], 0, v[178:179]
	global_load_lds_dwordx4 v[246:247], off
	s_mov_b32 m0, s18
	v_lshl_add_u64 v[250:251], s[12:13], 0, v[176:177]
	global_load_lds_dwordx4 v[248:249], off
	s_mov_b32 m0, s19
	s_nop 0
	global_load_lds_dwordx4 v[250:251], off
	ds_read_b128 v[162:165], v199 offset:16384
	ds_read_b128 v[166:169], v199 offset:17408
	ds_read_b128 v[184:187], v199 offset:18432
	ds_read_b128 v[188:191], v199 offset:19456
	ds_read_b128 v[192:195], v199 offset:20480
	ds_read_b128 v[200:203], v199 offset:21504
	ds_read_b128 v[204:207], v199 offset:22528
	ds_read_b128 v[236:239], v199 offset:23552
	s_waitcnt vmcnt(8)
	s_waitcnt lgkmcnt(0)
	s_barrier
	s_waitcnt lgkmcnt(0)
	v_mfma_f32_16x16x32_bf16 v[62:65], v[114:117], v[162:165], v[62:65]
	v_mfma_f32_16x16x32_bf16 v[58:61], v[122:125], v[162:165], v[58:61]
	v_mfma_f32_16x16x32_bf16 v[46:49], v[114:117], v[184:187], v[46:49]
	v_mfma_f32_16x16x32_bf16 v[42:45], v[122:125], v[184:187], v[42:45]
	v_mfma_f32_16x16x32_bf16 v[30:33], v[114:117], v[192:195], v[30:33]
	v_mfma_f32_16x16x32_bf16 v[26:29], v[122:125], v[192:195], v[26:29]
	v_mfma_f32_16x16x32_bf16 v[14:17], v[114:117], v[204:207], v[14:17]
	v_mfma_f32_16x16x32_bf16 v[10:13], v[122:125], v[204:207], v[10:13]
	v_mfma_f32_16x16x32_bf16 v[62:65], v[118:121], v[166:169], v[62:65]
	v_mfma_f32_16x16x32_bf16 v[58:61], v[126:129], v[166:169], v[58:61]
	v_mfma_f32_16x16x32_bf16 v[46:49], v[118:121], v[188:191], v[46:49]
	v_mfma_f32_16x16x32_bf16 v[42:45], v[126:129], v[188:191], v[42:45]
	v_mfma_f32_16x16x32_bf16 v[30:33], v[118:121], v[200:203], v[30:33]
	v_mfma_f32_16x16x32_bf16 v[26:29], v[126:129], v[200:203], v[26:29]
	v_mfma_f32_16x16x32_bf16 v[14:17], v[118:121], v[236:239], v[14:17]
	v_mfma_f32_16x16x32_bf16 v[10:13], v[126:129], v[236:239], v[10:13]
	v_mfma_f32_16x16x32_bf16 v[54:57], v[146:149], v[162:165], v[54:57]
	v_mfma_f32_16x16x32_bf16 v[50:53], v[154:157], v[162:165], v[50:53]
	v_mfma_f32_16x16x32_bf16 v[38:41], v[146:149], v[184:187], v[38:41]
	v_mfma_f32_16x16x32_bf16 v[34:37], v[154:157], v[184:187], v[34:37]
	v_mfma_f32_16x16x32_bf16 v[22:25], v[146:149], v[192:195], v[22:25]
	v_mfma_f32_16x16x32_bf16 v[18:21], v[154:157], v[192:195], v[18:21]
	v_mfma_f32_16x16x32_bf16 v[6:9], v[146:149], v[204:207], v[6:9]
	v_mfma_f32_16x16x32_bf16 v[2:5], v[154:157], v[204:207], v[2:5]
	v_mfma_f32_16x16x32_bf16 v[54:57], v[150:153], v[166:169], v[54:57]
	v_mfma_f32_16x16x32_bf16 v[50:53], v[158:161], v[166:169], v[50:53]
	v_mfma_f32_16x16x32_bf16 v[38:41], v[150:153], v[188:191], v[38:41]
	v_mfma_f32_16x16x32_bf16 v[34:37], v[158:161], v[188:191], v[34:37]
	v_mfma_f32_16x16x32_bf16 v[22:25], v[150:153], v[200:203], v[22:25]
	v_mfma_f32_16x16x32_bf16 v[18:21], v[158:161], v[200:203], v[18:21]
	v_mfma_f32_16x16x32_bf16 v[6:9], v[150:153], v[236:239], v[6:9]
	v_mfma_f32_16x16x32_bf16 v[2:5], v[158:161], v[236:239], v[2:5]
	s_barrier
	s_add_i32 s8, 0, 0x18000
	s_add_i32 s9, 0, 0x1c000
	s_add_u32 s12, s12, s20
	s_addc_u32 s13, s13, 0
	s_mov_b32 m0, s70
	v_lshl_add_u64 v[228:229], s[12:13], 0, v[178:179]
	global_load_lds_dwordx4 v[228:229], off
	v_lshl_add_u64 v[228:229], s[12:13], 0, v[176:177]
	s_mov_b32 m0, s71
	s_nop 0
	global_load_lds_dwordx4 v[228:229], off
	v_add_u32_e32 v126, s8, v197
	v_add_u32_e32 v158, s9, v197
	ds_read_b128 v[114:117], v126
	ds_read_b128 v[118:121], v126 offset:1024
	ds_read_b128 v[122:125], v126 offset:2048
	ds_read_b128 v[126:129], v126 offset:3072
	ds_read_b128 v[146:149], v158
	ds_read_b128 v[150:153], v158 offset:1024
	ds_read_b128 v[154:157], v158 offset:2048
	ds_read_b128 v[158:161], v158 offset:3072
	ds_read_b128 v[162:165], v199 offset:32768
	ds_read_b128 v[166:169], v199 offset:33792
	ds_read_b128 v[184:187], v199 offset:34816
	ds_read_b128 v[188:191], v199 offset:35840
	ds_read_b128 v[192:195], v199 offset:36864
	ds_read_b128 v[200:203], v199 offset:37888
	ds_read_b128 v[204:207], v199 offset:38912
	ds_read_b128 v[236:239], v199 offset:39936
	s_waitcnt vmcnt(8)
	s_waitcnt lgkmcnt(0)
	s_barrier
	s_waitcnt lgkmcnt(0)
	v_mfma_f32_16x16x32_bf16 v[142:145], v[114:117], v[162:165], v[142:145]
	v_mfma_f32_16x16x32_bf16 v[138:141], v[122:125], v[162:165], v[138:141]
	v_mfma_f32_16x16x32_bf16 v[110:113], v[114:117], v[184:187], v[110:113]
	v_mfma_f32_16x16x32_bf16 v[106:109], v[122:125], v[184:187], v[106:109]
	v_mfma_f32_16x16x32_bf16 v[94:97], v[114:117], v[192:195], v[94:97]
	v_mfma_f32_16x16x32_bf16 v[90:93], v[122:125], v[192:195], v[90:93]
	v_mfma_f32_16x16x32_bf16 v[78:81], v[114:117], v[204:207], v[78:81]
	v_mfma_f32_16x16x32_bf16 v[74:77], v[122:125], v[204:207], v[74:77]
	v_mfma_f32_16x16x32_bf16 v[142:145], v[118:121], v[166:169], v[142:145]
	v_mfma_f32_16x16x32_bf16 v[138:141], v[126:129], v[166:169], v[138:141]
	v_mfma_f32_16x16x32_bf16 v[110:113], v[118:121], v[188:191], v[110:113]
	v_mfma_f32_16x16x32_bf16 v[106:109], v[126:129], v[188:191], v[106:109]
	v_mfma_f32_16x16x32_bf16 v[94:97], v[118:121], v[200:203], v[94:97]
	v_mfma_f32_16x16x32_bf16 v[90:93], v[126:129], v[200:203], v[90:93]
	v_mfma_f32_16x16x32_bf16 v[78:81], v[118:121], v[236:239], v[78:81]
	v_mfma_f32_16x16x32_bf16 v[74:77], v[126:129], v[236:239], v[74:77]
	v_mfma_f32_16x16x32_bf16 v[134:137], v[146:149], v[162:165], v[134:137]
	v_mfma_f32_16x16x32_bf16 v[130:133], v[154:157], v[162:165], v[130:133]
	v_mfma_f32_16x16x32_bf16 v[102:105], v[146:149], v[184:187], v[102:105]
	v_mfma_f32_16x16x32_bf16 v[98:101], v[154:157], v[184:187], v[98:101]
	v_mfma_f32_16x16x32_bf16 v[86:89], v[146:149], v[192:195], v[86:89]
	v_mfma_f32_16x16x32_bf16 v[82:85], v[154:157], v[192:195], v[82:85]
	v_mfma_f32_16x16x32_bf16 v[70:73], v[146:149], v[204:207], v[70:73]
	v_mfma_f32_16x16x32_bf16 v[66:69], v[154:157], v[204:207], v[66:69]
	v_mfma_f32_16x16x32_bf16 v[134:137], v[150:153], v[166:169], v[134:137]
	v_mfma_f32_16x16x32_bf16 v[130:133], v[158:161], v[166:169], v[130:133]
	v_mfma_f32_16x16x32_bf16 v[102:105], v[150:153], v[188:191], v[102:105]
	v_mfma_f32_16x16x32_bf16 v[98:101], v[158:161], v[188:191], v[98:101]
	v_mfma_f32_16x16x32_bf16 v[86:89], v[150:153], v[200:203], v[86:89]
	v_mfma_f32_16x16x32_bf16 v[82:85], v[158:161], v[200:203], v[82:85]
	v_mfma_f32_16x16x32_bf16 v[70:73], v[150:153], v[236:239], v[70:73]
	v_mfma_f32_16x16x32_bf16 v[66:69], v[158:161], v[236:239], v[66:69]
	s_barrier
	s_add_i32 s8, s8, s17
	v_lshl_add_u64 v[228:229], v[240:241], 0, s[4:5]
	s_mov_b32 m0, s8
	s_nop 0
	global_load_lds_dwordx4 v[228:229], off
	v_lshl_add_u64 v[228:229], v[242:243], 0, s[4:5]
	s_add_i32 m0, s8, 0x2000
	s_add_i32 s8, s9, s17
	global_load_lds_dwordx4 v[228:229], off
	v_lshl_add_u64 v[228:229], v[244:245], 0, s[4:5]
	s_mov_b32 m0, s8
	s_nop 0
	global_load_lds_dwordx4 v[228:229], off
	v_lshl_add_u64 v[228:229], v[246:247], 0, s[4:5]
	s_add_i32 m0, s8, 0x2000
	s_nop 0
	global_load_lds_dwordx4 v[228:229], off
	v_lshl_add_u64 v[228:229], v[248:249], 0, s[4:5]
	s_mov_b32 m0, s88
	s_nop 0
	global_load_lds_dwordx4 v[228:229], off
	v_lshl_add_u64 v[228:229], v[250:251], 0, s[4:5]
	s_mov_b32 m0, s89
	s_nop 0
	global_load_lds_dwordx4 v[228:229], off
	ds_read_b128 v[162:165], v199 offset:49152
	ds_read_b128 v[166:169], v199 offset:50176
	ds_read_b128 v[184:187], v199 offset:51200
	ds_read_b128 v[188:191], v199 offset:52224
	ds_read_b128 v[192:195], v199 offset:53248
	ds_read_b128 v[200:203], v199 offset:54272
	ds_read_b128 v[204:207], v199 offset:55296
	ds_read_b128 v[236:239], v199 offset:56320
	s_waitcnt vmcnt(8)
	s_waitcnt lgkmcnt(0)
	s_barrier
	s_waitcnt lgkmcnt(0)
	v_mfma_f32_16x16x32_bf16 v[62:65], v[114:117], v[162:165], v[62:65]
	v_mfma_f32_16x16x32_bf16 v[58:61], v[122:125], v[162:165], v[58:61]
	v_mfma_f32_16x16x32_bf16 v[46:49], v[114:117], v[184:187], v[46:49]
	v_mfma_f32_16x16x32_bf16 v[42:45], v[122:125], v[184:187], v[42:45]
	v_mfma_f32_16x16x32_bf16 v[30:33], v[114:117], v[192:195], v[30:33]
	v_mfma_f32_16x16x32_bf16 v[26:29], v[122:125], v[192:195], v[26:29]
	v_mfma_f32_16x16x32_bf16 v[14:17], v[114:117], v[204:207], v[14:17]
	v_mfma_f32_16x16x32_bf16 v[10:13], v[122:125], v[204:207], v[10:13]
	v_mfma_f32_16x16x32_bf16 v[62:65], v[118:121], v[166:169], v[62:65]
	v_mfma_f32_16x16x32_bf16 v[58:61], v[126:129], v[166:169], v[58:61]
	v_mfma_f32_16x16x32_bf16 v[46:49], v[118:121], v[188:191], v[46:49]
	v_mfma_f32_16x16x32_bf16 v[42:45], v[126:129], v[188:191], v[42:45]
	v_mfma_f32_16x16x32_bf16 v[30:33], v[118:121], v[200:203], v[30:33]
	v_mfma_f32_16x16x32_bf16 v[26:29], v[126:129], v[200:203], v[26:29]
	v_mfma_f32_16x16x32_bf16 v[14:17], v[118:121], v[236:239], v[14:17]
	v_mfma_f32_16x16x32_bf16 v[10:13], v[126:129], v[236:239], v[10:13]
	v_mfma_f32_16x16x32_bf16 v[54:57], v[146:149], v[162:165], v[54:57]
	v_mfma_f32_16x16x32_bf16 v[50:53], v[154:157], v[162:165], v[50:53]
	v_mfma_f32_16x16x32_bf16 v[38:41], v[146:149], v[184:187], v[38:41]
	v_mfma_f32_16x16x32_bf16 v[34:37], v[154:157], v[184:187], v[34:37]
	v_mfma_f32_16x16x32_bf16 v[22:25], v[146:149], v[192:195], v[22:25]
	v_mfma_f32_16x16x32_bf16 v[18:21], v[154:157], v[192:195], v[18:21]
	v_mfma_f32_16x16x32_bf16 v[6:9], v[146:149], v[204:207], v[6:9]
	v_mfma_f32_16x16x32_bf16 v[2:5], v[154:157], v[204:207], v[2:5]
	v_mfma_f32_16x16x32_bf16 v[54:57], v[150:153], v[166:169], v[54:57]
	v_mfma_f32_16x16x32_bf16 v[50:53], v[158:161], v[166:169], v[50:53]
	v_mfma_f32_16x16x32_bf16 v[38:41], v[150:153], v[188:191], v[38:41]
	v_mfma_f32_16x16x32_bf16 v[34:37], v[158:161], v[188:191], v[34:37]
	v_mfma_f32_16x16x32_bf16 v[22:25], v[150:153], v[200:203], v[22:25]
	v_mfma_f32_16x16x32_bf16 v[18:21], v[158:161], v[200:203], v[18:21]
	v_mfma_f32_16x16x32_bf16 v[6:9], v[150:153], v[236:239], v[6:9]
	v_mfma_f32_16x16x32_bf16 v[2:5], v[158:161], v[236:239], v[2:5]
	s_barrier
	s_add_u32 s10, s10, 0x100
	s_addc_u32 s11, s11, 0
	s_add_u32 s14, s14, 0x100
	s_addc_u32 s15, s15, 0
	s_cmp_ge_u32 vcc_lo, s77
	s_mov_b32 s12, vcc_lo
	s_cbranch_scc0 .LBB0_194
	s_and_b64 vcc, exec, s[54:55]
	s_cbranch_vccz .LBB0_197
	s_barrier

.LBB0_219:
	s_add_i32 vcc_lo, s48, 2
	s_add_u32 s36, s18, 0x80
	s_addc_u32 s37, s19, 0
	s_add_i32 vcc_hi, 0, 0x10000
	s_cmp_eq_u32 s89, s48
	s_cselect_b32 s49, s17, s37
	s_cselect_b32 s48, s16, s36
	s_cselect_b32 s37, s45, s15
	s_cselect_b32 s36, s44, s11
	s_add_i32 s28, 0, 0x14000
	v_lshl_add_u64 v[168:169], s[18:19], 0, v[136:137]
	s_add_i32 m0, s54, 0xc000
	s_nop 0
	global_load_lds_dwordx4 v[168:169], off
	v_lshl_add_u64 v[168:169], s[18:19], 0, v[138:139]
	s_add_i32 m0, s54, 0xe000
	s_nop 0
	global_load_lds_dwordx4 v[168:169], off
	v_add_u32_e32 v156, vcc_hi, v141
	v_add_u32_e32 v168, s28, v141
	ds_read_b128 v[144:147], v156
	ds_read_b128 v[148:151], v156 offset:1024
	ds_read_b128 v[152:155], v156 offset:2048
	ds_read_b128 v[156:159], v156 offset:3072
	ds_read_b128 v[160:163], v168
	ds_read_b128 v[164:167], v168 offset:1024
	ds_read_b128 v[174:177], v168 offset:2048
	ds_read_b128 v[178:181], v168 offset:3072
	ds_read_b128 v[182:185], v143
	ds_read_b128 v[186:189], v143 offset:1024
	ds_read_b128 v[190:193], v143 offset:2048
	ds_read_b128 v[194:197], v143 offset:3072
	ds_read_b128 v[198:201], v143 offset:4096
	ds_read_b128 v[202:205], v143 offset:5120
	ds_read_b128 v[236:239], v143 offset:6144
	ds_read_b128 v[240:243], v143 offset:7168
	s_waitcnt vmcnt(8)
	s_waitcnt lgkmcnt(0)
	s_barrier
	s_waitcnt lgkmcnt(0)
	v_mfma_f32_16x16x32_bf16 v[126:129], v[144:147], v[182:185], v[126:129]
	v_mfma_f32_16x16x32_bf16 v[122:125], v[152:155], v[182:185], v[122:125]
	v_mfma_f32_16x16x32_bf16 v[118:121], v[144:147], v[190:193], v[118:121]
	v_mfma_f32_16x16x32_bf16 v[114:117], v[152:155], v[190:193], v[114:117]
	v_mfma_f32_16x16x32_bf16 v[106:109], v[144:147], v[198:201], v[106:109]
	v_mfma_f32_16x16x32_bf16 v[98:101], v[152:155], v[198:201], v[98:101]
	v_mfma_f32_16x16x32_bf16 v[90:93], v[144:147], v[236:239], v[90:93]
	v_mfma_f32_16x16x32_bf16 v[82:85], v[152:155], v[236:239], v[82:85]
	v_mfma_f32_16x16x32_bf16 v[126:129], v[148:151], v[186:189], v[126:129]
	v_mfma_f32_16x16x32_bf16 v[122:125], v[156:159], v[186:189], v[122:125]
	v_mfma_f32_16x16x32_bf16 v[118:121], v[148:151], v[194:197], v[118:121]
	v_mfma_f32_16x16x32_bf16 v[114:117], v[156:159], v[194:197], v[114:117]
	v_mfma_f32_16x16x32_bf16 v[106:109], v[148:151], v[202:205], v[106:109]
	v_mfma_f32_16x16x32_bf16 v[98:101], v[156:159], v[202:205], v[98:101]
	v_mfma_f32_16x16x32_bf16 v[90:93], v[148:151], v[240:243], v[90:93]
	v_mfma_f32_16x16x32_bf16 v[82:85], v[156:159], v[240:243], v[82:85]
	v_mfma_f32_16x16x32_bf16 v[110:113], v[160:163], v[182:185], v[110:113]
	v_mfma_f32_16x16x32_bf16 v[102:105], v[174:177], v[182:185], v[102:105]
	v_mfma_f32_16x16x32_bf16 v[94:97], v[160:163], v[190:193], v[94:97]
	v_mfma_f32_16x16x32_bf16 v[86:89], v[174:177], v[190:193], v[86:89]
	v_mfma_f32_16x16x32_bf16 v[78:81], v[160:163], v[198:201], v[78:81]
	v_mfma_f32_16x16x32_bf16 v[74:77], v[174:177], v[198:201], v[74:77]
	v_mfma_f32_16x16x32_bf16 v[70:73], v[160:163], v[236:239], v[70:73]
	v_mfma_f32_16x16x32_bf16 v[66:69], v[174:177], v[236:239], v[66:69]
	v_mfma_f32_16x16x32_bf16 v[110:113], v[164:167], v[186:189], v[110:113]
	v_mfma_f32_16x16x32_bf16 v[102:105], v[178:181], v[186:189], v[102:105]
	v_mfma_f32_16x16x32_bf16 v[94:97], v[164:167], v[194:197], v[94:97]
	v_mfma_f32_16x16x32_bf16 v[86:89], v[178:181], v[194:197], v[86:89]
	v_mfma_f32_16x16x32_bf16 v[78:81], v[164:167], v[202:205], v[78:81]
	v_mfma_f32_16x16x32_bf16 v[74:77], v[178:181], v[202:205], v[74:77]
	v_mfma_f32_16x16x32_bf16 v[70:73], v[164:167], v[240:243], v[70:73]
	v_mfma_f32_16x16x32_bf16 v[66:69], v[178:181], v[240:243], v[66:69]
	s_barrier
	s_add_i32 s29, vcc_hi, s41
	v_lshl_add_u64 v[168:169], s[36:37], 0, v[0:1]
	s_mov_b32 m0, s29
	s_nop 0
	global_load_lds_dwordx4 v[168:169], off
	s_add_i32 m0, s29, 0x2000
	v_lshl_add_u64 v[206:207], s[36:37], 0, v[130:131]
	s_add_u32 s36, s36, s20
	s_addc_u32 s37, s37, 0
	s_add_i32 s28, s28, s41
	global_load_lds_dwordx4 v[206:207], off
	v_lshl_add_u64 v[228:229], s[36:37], 0, v[0:1]
	s_mov_b32 m0, s28
	v_lshl_add_u64 v[244:245], s[36:37], 0, v[130:131]
	global_load_lds_dwordx4 v[228:229], off
	s_add_i32 m0, s28, 0x2000
	v_lshl_add_u64 v[246:247], s[48:49], 0, v[134:135]
	global_load_lds_dwordx4 v[244:245], off
	s_mov_b32 m0, s54
	v_lshl_add_u64 v[248:249], s[48:49], 0, v[132:133]
	global_load_lds_dwordx4 v[246:247], off
	s_mov_b32 m0, s55
	s_nop 0
	global_load_lds_dwordx4 v[248:249], off
	ds_read_b128 v[182:185], v143 offset:16384
	ds_read_b128 v[186:189], v143 offset:17408
	ds_read_b128 v[190:193], v143 offset:18432
	ds_read_b128 v[194:197], v143 offset:19456
	ds_read_b128 v[198:201], v143 offset:20480
	ds_read_b128 v[202:205], v143 offset:21504
	ds_read_b128 v[236:239], v143 offset:22528
	ds_read_b128 v[240:243], v143 offset:23552
	s_waitcnt vmcnt(8)
	s_waitcnt lgkmcnt(0)
	s_barrier
	s_waitcnt lgkmcnt(0)
	v_mfma_f32_16x16x32_bf16 v[62:65], v[144:147], v[182:185], v[62:65]
	v_mfma_f32_16x16x32_bf16 v[58:61], v[152:155], v[182:185], v[58:61]
	v_mfma_f32_16x16x32_bf16 v[54:57], v[144:147], v[190:193], v[54:57]
	v_mfma_f32_16x16x32_bf16 v[50:53], v[152:155], v[190:193], v[50:53]
	v_mfma_f32_16x16x32_bf16 v[42:45], v[144:147], v[198:201], v[42:45]
	v_mfma_f32_16x16x32_bf16 v[34:37], v[152:155], v[198:201], v[34:37]
	v_mfma_f32_16x16x32_bf16 v[26:29], v[144:147], v[236:239], v[26:29]
	v_mfma_f32_16x16x32_bf16 v[18:21], v[152:155], v[236:239], v[18:21]
	v_mfma_f32_16x16x32_bf16 v[62:65], v[148:151], v[186:189], v[62:65]
	v_mfma_f32_16x16x32_bf16 v[58:61], v[156:159], v[186:189], v[58:61]
	v_mfma_f32_16x16x32_bf16 v[54:57], v[148:151], v[194:197], v[54:57]
	v_mfma_f32_16x16x32_bf16 v[50:53], v[156:159], v[194:197], v[50:53]
	v_mfma_f32_16x16x32_bf16 v[42:45], v[148:151], v[202:205], v[42:45]
	v_mfma_f32_16x16x32_bf16 v[34:37], v[156:159], v[202:205], v[34:37]
	v_mfma_f32_16x16x32_bf16 v[26:29], v[148:151], v[240:243], v[26:29]
	v_mfma_f32_16x16x32_bf16 v[18:21], v[156:159], v[240:243], v[18:21]
	v_mfma_f32_16x16x32_bf16 v[46:49], v[160:163], v[182:185], v[46:49]
	v_mfma_f32_16x16x32_bf16 v[38:41], v[174:177], v[182:185], v[38:41]
	v_mfma_f32_16x16x32_bf16 v[30:33], v[160:163], v[190:193], v[30:33]
	v_mfma_f32_16x16x32_bf16 v[22:25], v[174:177], v[190:193], v[22:25]
	v_mfma_f32_16x16x32_bf16 v[14:17], v[160:163], v[198:201], v[14:17]
	v_mfma_f32_16x16x32_bf16 v[10:13], v[174:177], v[198:201], v[10:13]
	v_mfma_f32_16x16x32_bf16 v[6:9], v[160:163], v[236:239], v[6:9]
	v_mfma_f32_16x16x32_bf16 v[2:5], v[174:177], v[236:239], v[2:5]
	v_mfma_f32_16x16x32_bf16 v[46:49], v[164:167], v[186:189], v[46:49]
	v_mfma_f32_16x16x32_bf16 v[38:41], v[178:181], v[186:189], v[38:41]
	v_mfma_f32_16x16x32_bf16 v[30:33], v[164:167], v[194:197], v[30:33]
	v_mfma_f32_16x16x32_bf16 v[22:25], v[178:181], v[194:197], v[22:25]
	v_mfma_f32_16x16x32_bf16 v[14:17], v[164:167], v[202:205], v[14:17]
	v_mfma_f32_16x16x32_bf16 v[10:13], v[178:181], v[202:205], v[10:13]
	v_mfma_f32_16x16x32_bf16 v[6:9], v[164:167], v[240:243], v[6:9]
	v_mfma_f32_16x16x32_bf16 v[2:5], v[178:181], v[240:243], v[2:5]
	s_barrier
	s_add_i32 s28, 0, 0x18000
	s_add_i32 s29, 0, 0x1c000
	s_add_u32 s36, s48, s20
	s_addc_u32 s37, s49, 0
	s_mov_b32 m0, s70
	v_lshl_add_u64 v[250:251], s[36:37], 0, v[134:135]
	global_load_lds_dwordx4 v[250:251], off
	v_lshl_add_u64 v[250:251], s[36:37], 0, v[132:133]
	s_mov_b32 m0, s71
	s_nop 0
	global_load_lds_dwordx4 v[250:251], off
	v_add_u32_e32 v156, s28, v141
	v_add_u32_e32 v178, s29, v141
	ds_read_b128 v[144:147], v156
	ds_read_b128 v[148:151], v156 offset:1024
	ds_read_b128 v[152:155], v156 offset:2048
	ds_read_b128 v[156:159], v156 offset:3072
	ds_read_b128 v[160:163], v178
	ds_read_b128 v[164:167], v178 offset:1024
	ds_read_b128 v[174:177], v178 offset:2048
	ds_read_b128 v[178:181], v178 offset:3072
	ds_read_b128 v[182:185], v143 offset:32768
	ds_read_b128 v[186:189], v143 offset:33792
	ds_read_b128 v[190:193], v143 offset:34816
	ds_read_b128 v[194:197], v143 offset:35840
	ds_read_b128 v[198:201], v143 offset:36864
	ds_read_b128 v[202:205], v143 offset:37888
	ds_read_b128 v[236:239], v143 offset:38912
	ds_read_b128 v[240:243], v143 offset:39936
	s_waitcnt vmcnt(8)
	s_waitcnt lgkmcnt(0)
	s_barrier
	s_waitcnt lgkmcnt(0)
	v_mfma_f32_16x16x32_bf16 v[126:129], v[144:147], v[182:185], v[126:129]
	v_mfma_f32_16x16x32_bf16 v[122:125], v[152:155], v[182:185], v[122:125]
	v_mfma_f32_16x16x32_bf16 v[118:121], v[144:147], v[190:193], v[118:121]
	v_mfma_f32_16x16x32_bf16 v[114:117], v[152:155], v[190:193], v[114:117]
	v_mfma_f32_16x16x32_bf16 v[106:109], v[144:147], v[198:201], v[106:109]
	v_mfma_f32_16x16x32_bf16 v[98:101], v[152:155], v[198:201], v[98:101]
	v_mfma_f32_16x16x32_bf16 v[90:93], v[144:147], v[236:239], v[90:93]
	v_mfma_f32_16x16x32_bf16 v[82:85], v[152:155], v[236:239], v[82:85]
	v_mfma_f32_16x16x32_bf16 v[126:129], v[148:151], v[186:189], v[126:129]
	v_mfma_f32_16x16x32_bf16 v[122:125], v[156:159], v[186:189], v[122:125]
	v_mfma_f32_16x16x32_bf16 v[118:121], v[148:151], v[194:197], v[118:121]
	v_mfma_f32_16x16x32_bf16 v[114:117], v[156:159], v[194:197], v[114:117]
	v_mfma_f32_16x16x32_bf16 v[106:109], v[148:151], v[202:205], v[106:109]
	v_mfma_f32_16x16x32_bf16 v[98:101], v[156:159], v[202:205], v[98:101]
	v_mfma_f32_16x16x32_bf16 v[90:93], v[148:151], v[240:243], v[90:93]
	v_mfma_f32_16x16x32_bf16 v[82:85], v[156:159], v[240:243], v[82:85]
	v_mfma_f32_16x16x32_bf16 v[110:113], v[160:163], v[182:185], v[110:113]
	v_mfma_f32_16x16x32_bf16 v[102:105], v[174:177], v[182:185], v[102:105]
	v_mfma_f32_16x16x32_bf16 v[94:97], v[160:163], v[190:193], v[94:97]
	v_mfma_f32_16x16x32_bf16 v[86:89], v[174:177], v[190:193], v[86:89]
	v_mfma_f32_16x16x32_bf16 v[78:81], v[160:163], v[198:201], v[78:81]
	v_mfma_f32_16x16x32_bf16 v[74:77], v[174:177], v[198:201], v[74:77]
	v_mfma_f32_16x16x32_bf16 v[70:73], v[160:163], v[236:239], v[70:73]
	v_mfma_f32_16x16x32_bf16 v[66:69], v[174:177], v[236:239], v[66:69]
	v_mfma_f32_16x16x32_bf16 v[110:113], v[164:167], v[186:189], v[110:113]
	v_mfma_f32_16x16x32_bf16 v[102:105], v[178:181], v[186:189], v[102:105]
	v_mfma_f32_16x16x32_bf16 v[94:97], v[164:167], v[194:197], v[94:97]
	v_mfma_f32_16x16x32_bf16 v[86:89], v[178:181], v[194:197], v[86:89]
	v_mfma_f32_16x16x32_bf16 v[78:81], v[164:167], v[202:205], v[78:81]
	v_mfma_f32_16x16x32_bf16 v[74:77], v[178:181], v[202:205], v[74:77]
	v_mfma_f32_16x16x32_bf16 v[70:73], v[164:167], v[240:243], v[70:73]
	v_mfma_f32_16x16x32_bf16 v[66:69], v[178:181], v[240:243], v[66:69]
	s_barrier
	s_add_i32 s28, s28, s41
	v_lshl_add_u64 v[168:169], v[168:169], 0, s[4:5]
	s_mov_b32 m0, s28
	s_nop 0
	global_load_lds_dwordx4 v[168:169], off
	v_lshl_add_u64 v[168:169], v[206:207], 0, s[4:5]
	s_add_i32 m0, s28, 0x2000
	s_add_i32 s28, s29, s41
	global_load_lds_dwordx4 v[168:169], off
	v_lshl_add_u64 v[168:169], v[228:229], 0, s[4:5]
	s_mov_b32 m0, s28
	s_nop 0
	global_load_lds_dwordx4 v[168:169], off
	v_lshl_add_u64 v[168:169], v[244:245], 0, s[4:5]
	s_add_i32 m0, s28, 0x2000
	s_nop 0
	global_load_lds_dwordx4 v[168:169], off
	v_lshl_add_u64 v[168:169], v[246:247], 0, s[4:5]
	s_mov_b32 m0, s83
	s_nop 0
	global_load_lds_dwordx4 v[168:169], off
	v_lshl_add_u64 v[168:169], v[248:249], 0, s[4:5]
	s_mov_b32 m0, s85
	s_nop 0
	global_load_lds_dwordx4 v[168:169], off
	ds_read_b128 v[182:185], v143 offset:49152
	ds_read_b128 v[186:189], v143 offset:50176
	ds_read_b128 v[190:193], v143 offset:51200
	ds_read_b128 v[194:197], v143 offset:52224
	ds_read_b128 v[198:201], v143 offset:53248
	ds_read_b128 v[202:205], v143 offset:54272
	ds_read_b128 v[236:239], v143 offset:55296
	ds_read_b128 v[240:243], v143 offset:56320
	s_waitcnt vmcnt(8)
	s_waitcnt lgkmcnt(0)
	s_barrier
	s_waitcnt lgkmcnt(0)
	v_mfma_f32_16x16x32_bf16 v[62:65], v[144:147], v[182:185], v[62:65]
	v_mfma_f32_16x16x32_bf16 v[58:61], v[152:155], v[182:185], v[58:61]
	v_mfma_f32_16x16x32_bf16 v[54:57], v[144:147], v[190:193], v[54:57]
	v_mfma_f32_16x16x32_bf16 v[50:53], v[152:155], v[190:193], v[50:53]
	v_mfma_f32_16x16x32_bf16 v[42:45], v[144:147], v[198:201], v[42:45]
	v_mfma_f32_16x16x32_bf16 v[34:37], v[152:155], v[198:201], v[34:37]
	v_mfma_f32_16x16x32_bf16 v[26:29], v[144:147], v[236:239], v[26:29]
	v_mfma_f32_16x16x32_bf16 v[18:21], v[152:155], v[236:239], v[18:21]
	v_mfma_f32_16x16x32_bf16 v[62:65], v[148:151], v[186:189], v[62:65]
	v_mfma_f32_16x16x32_bf16 v[58:61], v[156:159], v[186:189], v[58:61]
	v_mfma_f32_16x16x32_bf16 v[54:57], v[148:151], v[194:197], v[54:57]
	v_mfma_f32_16x16x32_bf16 v[50:53], v[156:159], v[194:197], v[50:53]
	v_mfma_f32_16x16x32_bf16 v[42:45], v[148:151], v[202:205], v[42:45]
	v_mfma_f32_16x16x32_bf16 v[34:37], v[156:159], v[202:205], v[34:37]
	v_mfma_f32_16x16x32_bf16 v[26:29], v[148:151], v[240:243], v[26:29]
	v_mfma_f32_16x16x32_bf16 v[18:21], v[156:159], v[240:243], v[18:21]
	v_mfma_f32_16x16x32_bf16 v[46:49], v[160:163], v[182:185], v[46:49]
	v_mfma_f32_16x16x32_bf16 v[38:41], v[174:177], v[182:185], v[38:41]
	v_mfma_f32_16x16x32_bf16 v[30:33], v[160:163], v[190:193], v[30:33]
	v_mfma_f32_16x16x32_bf16 v[22:25], v[174:177], v[190:193], v[22:25]
	v_mfma_f32_16x16x32_bf16 v[14:17], v[160:163], v[198:201], v[14:17]
	v_mfma_f32_16x16x32_bf16 v[10:13], v[174:177], v[198:201], v[10:13]
	v_mfma_f32_16x16x32_bf16 v[6:9], v[160:163], v[236:239], v[6:9]
	v_mfma_f32_16x16x32_bf16 v[2:5], v[174:177], v[236:239], v[2:5]
	v_mfma_f32_16x16x32_bf16 v[46:49], v[164:167], v[186:189], v[46:49]
	v_mfma_f32_16x16x32_bf16 v[38:41], v[178:181], v[186:189], v[38:41]
	v_mfma_f32_16x16x32_bf16 v[30:33], v[164:167], v[194:197], v[30:33]
	v_mfma_f32_16x16x32_bf16 v[22:25], v[178:181], v[194:197], v[22:25]
	v_mfma_f32_16x16x32_bf16 v[14:17], v[164:167], v[202:205], v[14:17]
	v_mfma_f32_16x16x32_bf16 v[10:13], v[178:181], v[202:205], v[10:13]
	v_mfma_f32_16x16x32_bf16 v[6:9], v[164:167], v[240:243], v[6:9]
	v_mfma_f32_16x16x32_bf16 v[2:5], v[178:181], v[240:243], v[2:5]
	s_barrier
	s_add_u32 s18, s18, 0x100
	s_addc_u32 s19, s19, 0
	s_add_u32 s11, s11, 0x100
	s_addc_u32 s15, s15, 0
	s_cmp_ge_u32 vcc_lo, s79
	s_mov_b32 s48, vcc_lo
	s_cbranch_scc0 .LBB0_219
	s_and_b64 vcc, exec, s[8:9]
	s_cbranch_vccz .LBB0_222
	s_barrier

.LBB0_437:
	s_add_u32 s12, s10, 0xfffc0080
	s_addc_u32 s13, s11, -1
	s_add_i32 s36, 0, 0x10000
	s_cmp_eq_u32 s78, 12
	s_cselect_b32 s15, s9, s13
	s_cselect_b32 s14, s45, s12
	s_cselect_b32 s13, s46, s77
	s_cselect_b32 s12, s47, s49
	s_add_i32 s37, 0, 0x14000
	v_lshl_add_u64 v[168:169], s[10:11], 0, v[136:137]
	s_add_i32 m0, s19, 0xc000
	s_nop 0
	global_load_lds_dwordx4 v[168:169], off
	v_lshl_add_u64 v[168:169], s[10:11], 0, v[138:139]
	s_add_i32 m0, s19, 0xe000
	s_nop 0
	global_load_lds_dwordx4 v[168:169], off
	v_add_u32_e32 v156, s36, v145
	v_add_u32_e32 v168, s37, v145
	ds_read_b128 v[140:143], v156
	ds_read_b128 v[148:151], v156 offset:1024
	ds_read_b128 v[152:155], v156 offset:2048
	ds_read_b128 v[156:159], v156 offset:3072
	ds_read_b128 v[160:163], v168
	ds_read_b128 v[164:167], v168 offset:1024
	ds_read_b128 v[174:177], v168 offset:2048
	ds_read_b128 v[178:181], v168 offset:3072
	ds_read_b128 v[182:185], v147
	ds_read_b128 v[186:189], v147 offset:1024
	ds_read_b128 v[190:193], v147 offset:2048
	ds_read_b128 v[194:197], v147 offset:3072
	ds_read_b128 v[198:201], v147 offset:4096
	ds_read_b128 v[202:205], v147 offset:5120
	ds_read_b128 v[236:239], v147 offset:6144
	ds_read_b128 v[240:243], v147 offset:7168
	s_waitcnt vmcnt(8)
	s_waitcnt lgkmcnt(0)
	s_barrier
	s_waitcnt lgkmcnt(0)
	v_mfma_f32_16x16x32_bf16 v[126:129], v[140:143], v[182:185], v[126:129]
	v_mfma_f32_16x16x32_bf16 v[122:125], v[152:155], v[182:185], v[122:125]
	v_mfma_f32_16x16x32_bf16 v[110:113], v[140:143], v[190:193], v[110:113]
	v_mfma_f32_16x16x32_bf16 v[106:109], v[152:155], v[190:193], v[106:109]
	v_mfma_f32_16x16x32_bf16 v[94:97], v[140:143], v[198:201], v[94:97]
	v_mfma_f32_16x16x32_bf16 v[90:93], v[152:155], v[198:201], v[90:93]
	v_mfma_f32_16x16x32_bf16 v[78:81], v[140:143], v[236:239], v[78:81]
	v_mfma_f32_16x16x32_bf16 v[74:77], v[152:155], v[236:239], v[74:77]
	v_mfma_f32_16x16x32_bf16 v[126:129], v[148:151], v[186:189], v[126:129]
	v_mfma_f32_16x16x32_bf16 v[122:125], v[156:159], v[186:189], v[122:125]
	v_mfma_f32_16x16x32_bf16 v[110:113], v[148:151], v[194:197], v[110:113]
	v_mfma_f32_16x16x32_bf16 v[106:109], v[156:159], v[194:197], v[106:109]
	v_mfma_f32_16x16x32_bf16 v[94:97], v[148:151], v[202:205], v[94:97]
	v_mfma_f32_16x16x32_bf16 v[90:93], v[156:159], v[202:205], v[90:93]
	v_mfma_f32_16x16x32_bf16 v[78:81], v[148:151], v[240:243], v[78:81]
	v_mfma_f32_16x16x32_bf16 v[74:77], v[156:159], v[240:243], v[74:77]
	v_mfma_f32_16x16x32_bf16 v[118:121], v[160:163], v[182:185], v[118:121]
	v_mfma_f32_16x16x32_bf16 v[114:117], v[174:177], v[182:185], v[114:117]
	v_mfma_f32_16x16x32_bf16 v[102:105], v[160:163], v[190:193], v[102:105]
	v_mfma_f32_16x16x32_bf16 v[98:101], v[174:177], v[190:193], v[98:101]
	v_mfma_f32_16x16x32_bf16 v[86:89], v[160:163], v[198:201], v[86:89]
	v_mfma_f32_16x16x32_bf16 v[82:85], v[174:177], v[198:201], v[82:85]
	v_mfma_f32_16x16x32_bf16 v[70:73], v[160:163], v[236:239], v[70:73]
	v_mfma_f32_16x16x32_bf16 v[66:69], v[174:177], v[236:239], v[66:69]
	v_mfma_f32_16x16x32_bf16 v[118:121], v[164:167], v[186:189], v[118:121]
	v_mfma_f32_16x16x32_bf16 v[114:117], v[178:181], v[186:189], v[114:117]
	v_mfma_f32_16x16x32_bf16 v[102:105], v[164:167], v[194:197], v[102:105]
	v_mfma_f32_16x16x32_bf16 v[98:101], v[178:181], v[194:197], v[98:101]
	v_mfma_f32_16x16x32_bf16 v[86:89], v[164:167], v[202:205], v[86:89]
	v_mfma_f32_16x16x32_bf16 v[82:85], v[178:181], v[202:205], v[82:85]
	v_mfma_f32_16x16x32_bf16 v[70:73], v[164:167], v[240:243], v[70:73]
	v_mfma_f32_16x16x32_bf16 v[66:69], v[178:181], v[240:243], v[66:69]
	s_barrier
	s_add_i32 s36, s36, s18
	v_lshl_add_u64 v[168:169], s[12:13], 0, v[0:1]
	s_mov_b32 m0, s36
	s_nop 0
	global_load_lds_dwordx4 v[168:169], off
	s_add_i32 m0, s36, 0x2000
	s_add_u32 s82, s12, 0x40000
	v_lshl_add_u64 v[206:207], s[12:13], 0, v[130:131]
	s_addc_u32 s83, s13, 0
	s_add_i32 s36, s37, s18
	global_load_lds_dwordx4 v[206:207], off
	v_lshl_add_u64 v[244:245], s[82:83], 0, v[0:1]
	s_mov_b32 m0, s36
	v_lshl_add_u64 v[246:247], s[14:15], 0, v[132:133]
	global_load_lds_dwordx4 v[244:245], off
	v_lshl_add_u64 v[244:245], s[82:83], 0, v[130:131]
	s_add_i32 m0, s36, 0x2000
	s_nop 0
	global_load_lds_dwordx4 v[244:245], off
	v_lshl_add_u64 v[244:245], s[14:15], 0, v[134:135]
	s_mov_b32 m0, s19
	s_nop 0
	global_load_lds_dwordx4 v[244:245], off
	s_mov_b32 m0, s34
	s_nop 0
	global_load_lds_dwordx4 v[246:247], off
	ds_read_b128 v[182:185], v147 offset:16384
	ds_read_b128 v[186:189], v147 offset:17408
	ds_read_b128 v[190:193], v147 offset:18432
	ds_read_b128 v[194:197], v147 offset:19456
	ds_read_b128 v[198:201], v147 offset:20480
	ds_read_b128 v[202:205], v147 offset:21504
	ds_read_b128 v[236:239], v147 offset:22528
	ds_read_b128 v[240:243], v147 offset:23552
	s_waitcnt vmcnt(8)
	s_waitcnt lgkmcnt(0)
	s_barrier
	s_waitcnt lgkmcnt(0)
	v_mfma_f32_16x16x32_bf16 v[62:65], v[140:143], v[182:185], v[62:65]
	v_mfma_f32_16x16x32_bf16 v[58:61], v[152:155], v[182:185], v[58:61]
	v_mfma_f32_16x16x32_bf16 v[46:49], v[140:143], v[190:193], v[46:49]
	v_mfma_f32_16x16x32_bf16 v[42:45], v[152:155], v[190:193], v[42:45]
	v_mfma_f32_16x16x32_bf16 v[30:33], v[140:143], v[198:201], v[30:33]
	v_mfma_f32_16x16x32_bf16 v[26:29], v[152:155], v[198:201], v[26:29]
	v_mfma_f32_16x16x32_bf16 v[14:17], v[140:143], v[236:239], v[14:17]
	v_mfma_f32_16x16x32_bf16 v[10:13], v[152:155], v[236:239], v[10:13]
	v_mfma_f32_16x16x32_bf16 v[62:65], v[148:151], v[186:189], v[62:65]
	v_mfma_f32_16x16x32_bf16 v[58:61], v[156:159], v[186:189], v[58:61]
	v_mfma_f32_16x16x32_bf16 v[46:49], v[148:151], v[194:197], v[46:49]
	v_mfma_f32_16x16x32_bf16 v[42:45], v[156:159], v[194:197], v[42:45]
	v_mfma_f32_16x16x32_bf16 v[30:33], v[148:151], v[202:205], v[30:33]
	v_mfma_f32_16x16x32_bf16 v[26:29], v[156:159], v[202:205], v[26:29]
	v_mfma_f32_16x16x32_bf16 v[14:17], v[148:151], v[240:243], v[14:17]
	v_mfma_f32_16x16x32_bf16 v[10:13], v[156:159], v[240:243], v[10:13]
	v_mfma_f32_16x16x32_bf16 v[54:57], v[160:163], v[182:185], v[54:57]
	v_mfma_f32_16x16x32_bf16 v[50:53], v[174:177], v[182:185], v[50:53]
	v_mfma_f32_16x16x32_bf16 v[38:41], v[160:163], v[190:193], v[38:41]
	v_mfma_f32_16x16x32_bf16 v[34:37], v[174:177], v[190:193], v[34:37]
	v_mfma_f32_16x16x32_bf16 v[22:25], v[160:163], v[198:201], v[22:25]
	v_mfma_f32_16x16x32_bf16 v[18:21], v[174:177], v[198:201], v[18:21]
	v_mfma_f32_16x16x32_bf16 v[6:9], v[160:163], v[236:239], v[6:9]
	v_mfma_f32_16x16x32_bf16 v[2:5], v[174:177], v[236:239], v[2:5]
	v_mfma_f32_16x16x32_bf16 v[54:57], v[164:167], v[186:189], v[54:57]
	v_mfma_f32_16x16x32_bf16 v[50:53], v[178:181], v[186:189], v[50:53]
	v_mfma_f32_16x16x32_bf16 v[38:41], v[164:167], v[194:197], v[38:41]
	v_mfma_f32_16x16x32_bf16 v[34:37], v[178:181], v[194:197], v[34:37]
	v_mfma_f32_16x16x32_bf16 v[22:25], v[164:167], v[202:205], v[22:25]
	v_mfma_f32_16x16x32_bf16 v[18:21], v[178:181], v[202:205], v[18:21]
	v_mfma_f32_16x16x32_bf16 v[6:9], v[164:167], v[240:243], v[6:9]
	v_mfma_f32_16x16x32_bf16 v[2:5], v[178:181], v[240:243], v[2:5]
	s_barrier
	s_add_i32 s36, 0, 0x18000
	s_add_i32 s37, 0, 0x1c000
	s_add_u32 s14, s14, 0x40000
	s_addc_u32 s15, s15, 0
	s_mov_b32 m0, s54
	v_lshl_add_u64 v[248:249], s[14:15], 0, v[134:135]
	global_load_lds_dwordx4 v[248:249], off
	v_lshl_add_u64 v[248:249], s[14:15], 0, v[132:133]
	s_mov_b32 m0, s55
	s_nop 0
	global_load_lds_dwordx4 v[248:249], off
	v_add_u32_e32 v156, s36, v145
	v_add_u32_e32 v178, s37, v145
	ds_read_b128 v[140:143], v156
	ds_read_b128 v[148:151], v156 offset:1024
	ds_read_b128 v[152:155], v156 offset:2048
	ds_read_b128 v[156:159], v156 offset:3072
	ds_read_b128 v[160:163], v178
	ds_read_b128 v[164:167], v178 offset:1024
	ds_read_b128 v[174:177], v178 offset:2048
	ds_read_b128 v[178:181], v178 offset:3072
	ds_read_b128 v[182:185], v147 offset:32768
	ds_read_b128 v[186:189], v147 offset:33792
	ds_read_b128 v[190:193], v147 offset:34816
	ds_read_b128 v[194:197], v147 offset:35840
	ds_read_b128 v[198:201], v147 offset:36864
	ds_read_b128 v[202:205], v147 offset:37888
	ds_read_b128 v[236:239], v147 offset:38912
	ds_read_b128 v[240:243], v147 offset:39936
	s_waitcnt vmcnt(8)
	s_waitcnt lgkmcnt(0)
	s_barrier
	s_waitcnt lgkmcnt(0)
	v_mfma_f32_16x16x32_bf16 v[126:129], v[140:143], v[182:185], v[126:129]
	v_mfma_f32_16x16x32_bf16 v[122:125], v[152:155], v[182:185], v[122:125]
	v_mfma_f32_16x16x32_bf16 v[110:113], v[140:143], v[190:193], v[110:113]
	v_mfma_f32_16x16x32_bf16 v[106:109], v[152:155], v[190:193], v[106:109]
	v_mfma_f32_16x16x32_bf16 v[94:97], v[140:143], v[198:201], v[94:97]
	v_mfma_f32_16x16x32_bf16 v[90:93], v[152:155], v[198:201], v[90:93]
	v_mfma_f32_16x16x32_bf16 v[78:81], v[140:143], v[236:239], v[78:81]
	v_mfma_f32_16x16x32_bf16 v[74:77], v[152:155], v[236:239], v[74:77]
	v_mfma_f32_16x16x32_bf16 v[126:129], v[148:151], v[186:189], v[126:129]
	v_mfma_f32_16x16x32_bf16 v[122:125], v[156:159], v[186:189], v[122:125]
	v_mfma_f32_16x16x32_bf16 v[110:113], v[148:151], v[194:197], v[110:113]
	v_mfma_f32_16x16x32_bf16 v[106:109], v[156:159], v[194:197], v[106:109]
	v_mfma_f32_16x16x32_bf16 v[94:97], v[148:151], v[202:205], v[94:97]
	v_mfma_f32_16x16x32_bf16 v[90:93], v[156:159], v[202:205], v[90:93]
	v_mfma_f32_16x16x32_bf16 v[78:81], v[148:151], v[240:243], v[78:81]
	v_mfma_f32_16x16x32_bf16 v[74:77], v[156:159], v[240:243], v[74:77]
	v_mfma_f32_16x16x32_bf16 v[118:121], v[160:163], v[182:185], v[118:121]
	v_mfma_f32_16x16x32_bf16 v[114:117], v[174:177], v[182:185], v[114:117]
	v_mfma_f32_16x16x32_bf16 v[102:105], v[160:163], v[190:193], v[102:105]
	v_mfma_f32_16x16x32_bf16 v[98:101], v[174:177], v[190:193], v[98:101]
	v_mfma_f32_16x16x32_bf16 v[86:89], v[160:163], v[198:201], v[86:89]
	v_mfma_f32_16x16x32_bf16 v[82:85], v[174:177], v[198:201], v[82:85]
	v_mfma_f32_16x16x32_bf16 v[70:73], v[160:163], v[236:239], v[70:73]
	v_mfma_f32_16x16x32_bf16 v[66:69], v[174:177], v[236:239], v[66:69]
	v_mfma_f32_16x16x32_bf16 v[118:121], v[164:167], v[186:189], v[118:121]
	v_mfma_f32_16x16x32_bf16 v[114:117], v[178:181], v[186:189], v[114:117]
	v_mfma_f32_16x16x32_bf16 v[102:105], v[164:167], v[194:197], v[102:105]
	v_mfma_f32_16x16x32_bf16 v[98:101], v[178:181], v[194:197], v[98:101]
	v_mfma_f32_16x16x32_bf16 v[86:89], v[164:167], v[202:205], v[86:89]
	v_mfma_f32_16x16x32_bf16 v[82:85], v[178:181], v[202:205], v[82:85]
	v_mfma_f32_16x16x32_bf16 v[70:73], v[164:167], v[240:243], v[70:73]
	v_mfma_f32_16x16x32_bf16 v[66:69], v[178:181], v[240:243], v[66:69]
	s_barrier
	s_add_i32 s14, s36, s18
	v_lshl_add_u64 v[168:169], v[168:169], 0, s[4:5]
	s_mov_b32 m0, s14
	s_nop 0
	global_load_lds_dwordx4 v[168:169], off
	s_add_i32 m0, s14, 0x2000
	s_add_u32 s12, s12, 0x40080
	v_lshl_add_u64 v[168:169], v[206:207], 0, s[4:5]
	s_addc_u32 s13, s13, 0
	s_add_i32 s14, s37, s18
	global_load_lds_dwordx4 v[168:169], off
	v_lshl_add_u64 v[168:169], s[12:13], 0, v[0:1]
	s_mov_b32 m0, s14
	s_nop 0
	global_load_lds_dwordx4 v[168:169], off
	v_lshl_add_u64 v[168:169], s[12:13], 0, v[130:131]
	s_add_i32 m0, s14, 0x2000
	s_nop 0
	global_load_lds_dwordx4 v[168:169], off
	v_lshl_add_u64 v[168:169], v[244:245], 0, s[4:5]
	s_mov_b32 m0, s70
	s_nop 0
	global_load_lds_dwordx4 v[168:169], off
	v_lshl_add_u64 v[168:169], v[246:247], 0, s[4:5]
	s_mov_b32 m0, s71
	s_nop 0
	global_load_lds_dwordx4 v[168:169], off
	ds_read_b128 v[182:185], v147 offset:49152
	ds_read_b128 v[186:189], v147 offset:50176
	ds_read_b128 v[190:193], v147 offset:51200
	ds_read_b128 v[194:197], v147 offset:52224
	ds_read_b128 v[198:201], v147 offset:53248
	ds_read_b128 v[202:205], v147 offset:54272
	ds_read_b128 v[236:239], v147 offset:55296
	ds_read_b128 v[240:243], v147 offset:56320
	s_waitcnt vmcnt(8)
	s_waitcnt lgkmcnt(0)
	s_barrier
	s_waitcnt lgkmcnt(0)
	v_mfma_f32_16x16x32_bf16 v[62:65], v[140:143], v[182:185], v[62:65]
	v_mfma_f32_16x16x32_bf16 v[58:61], v[152:155], v[182:185], v[58:61]
	v_mfma_f32_16x16x32_bf16 v[46:49], v[140:143], v[190:193], v[46:49]
	v_mfma_f32_16x16x32_bf16 v[42:45], v[152:155], v[190:193], v[42:45]
	v_mfma_f32_16x16x32_bf16 v[30:33], v[140:143], v[198:201], v[30:33]
	v_mfma_f32_16x16x32_bf16 v[26:29], v[152:155], v[198:201], v[26:29]
	v_mfma_f32_16x16x32_bf16 v[14:17], v[140:143], v[236:239], v[14:17]
	v_mfma_f32_16x16x32_bf16 v[10:13], v[152:155], v[236:239], v[10:13]
	v_mfma_f32_16x16x32_bf16 v[62:65], v[148:151], v[186:189], v[62:65]
	v_mfma_f32_16x16x32_bf16 v[58:61], v[156:159], v[186:189], v[58:61]
	v_mfma_f32_16x16x32_bf16 v[46:49], v[148:151], v[194:197], v[46:49]
	v_mfma_f32_16x16x32_bf16 v[42:45], v[156:159], v[194:197], v[42:45]
	v_mfma_f32_16x16x32_bf16 v[30:33], v[148:151], v[202:205], v[30:33]
	v_mfma_f32_16x16x32_bf16 v[26:29], v[156:159], v[202:205], v[26:29]
	v_mfma_f32_16x16x32_bf16 v[14:17], v[148:151], v[240:243], v[14:17]
	v_mfma_f32_16x16x32_bf16 v[10:13], v[156:159], v[240:243], v[10:13]
	v_mfma_f32_16x16x32_bf16 v[54:57], v[160:163], v[182:185], v[54:57]
	v_mfma_f32_16x16x32_bf16 v[50:53], v[174:177], v[182:185], v[50:53]
	v_mfma_f32_16x16x32_bf16 v[38:41], v[160:163], v[190:193], v[38:41]
	v_mfma_f32_16x16x32_bf16 v[34:37], v[174:177], v[190:193], v[34:37]
	v_mfma_f32_16x16x32_bf16 v[22:25], v[160:163], v[198:201], v[22:25]
	v_mfma_f32_16x16x32_bf16 v[18:21], v[174:177], v[198:201], v[18:21]
	v_mfma_f32_16x16x32_bf16 v[6:9], v[160:163], v[236:239], v[6:9]
	v_mfma_f32_16x16x32_bf16 v[2:5], v[174:177], v[236:239], v[2:5]
	v_mfma_f32_16x16x32_bf16 v[54:57], v[164:167], v[186:189], v[54:57]
	v_mfma_f32_16x16x32_bf16 v[50:53], v[178:181], v[186:189], v[50:53]
	v_mfma_f32_16x16x32_bf16 v[38:41], v[164:167], v[194:197], v[38:41]
	v_mfma_f32_16x16x32_bf16 v[34:37], v[178:181], v[194:197], v[34:37]
	v_mfma_f32_16x16x32_bf16 v[22:25], v[164:167], v[202:205], v[22:25]
	v_mfma_f32_16x16x32_bf16 v[18:21], v[178:181], v[202:205], v[18:21]
	v_mfma_f32_16x16x32_bf16 v[6:9], v[164:167], v[240:243], v[6:9]
	v_mfma_f32_16x16x32_bf16 v[2:5], v[178:181], v[240:243], v[2:5]
	s_barrier
	s_add_i32 s78, s78, 2
	s_add_u32 s10, s10, 0x100
	s_addc_u32 s11, s11, 0
	s_add_u32 s49, s49, 0x100
	s_addc_u32 s77, s77, 0
	s_cmp_gt_u32 s78, 13
	s_cbranch_scc0 .LBB0_437
	s_and_b64 vcc, exec, s[6:7]
	s_cbranch_vccz .LBB0_440
	s_barrier

.LBB0_493:
	s_add_u32 s16, s14, 0xfffc0080
	s_addc_u32 s17, s15, -1
	s_add_i32 s36, 0, 0x10000
	s_cmp_eq_u32 s46, 12
	s_cselect_b32 s19, s11, s17
	s_cselect_b32 s18, s13, s16
	s_cselect_b32 s17, s40, s45
	s_cselect_b32 s16, s41, s44
	s_add_i32 s37, 0, 0x14000
	v_lshl_add_u64 v[168:169], s[14:15], 0, v[136:137]
	s_add_i32 m0, s74, 0xc000
	s_nop 0
	global_load_lds_dwordx4 v[168:169], off
	v_lshl_add_u64 v[168:169], s[14:15], 0, v[138:139]
	s_add_i32 m0, s74, 0xe000
	s_nop 0
	global_load_lds_dwordx4 v[168:169], off
	v_add_u32_e32 v156, s36, v145
	v_add_u32_e32 v168, s37, v145
	ds_read_b128 v[140:143], v156
	ds_read_b128 v[148:151], v156 offset:1024
	ds_read_b128 v[152:155], v156 offset:2048
	ds_read_b128 v[156:159], v156 offset:3072
	ds_read_b128 v[160:163], v168
	ds_read_b128 v[164:167], v168 offset:1024
	ds_read_b128 v[174:177], v168 offset:2048
	ds_read_b128 v[178:181], v168 offset:3072
	ds_read_b128 v[182:185], v147
	ds_read_b128 v[186:189], v147 offset:1024
	ds_read_b128 v[190:193], v147 offset:2048
	ds_read_b128 v[194:197], v147 offset:3072
	ds_read_b128 v[198:201], v147 offset:4096
	ds_read_b128 v[202:205], v147 offset:5120
	ds_read_b128 v[236:239], v147 offset:6144
	ds_read_b128 v[240:243], v147 offset:7168
	s_waitcnt vmcnt(8)
	s_waitcnt lgkmcnt(0)
	s_barrier
	s_waitcnt lgkmcnt(0)
	v_mfma_f32_16x16x32_bf16 v[126:129], v[140:143], v[182:185], v[126:129]
	v_mfma_f32_16x16x32_bf16 v[122:125], v[152:155], v[182:185], v[122:125]
	v_mfma_f32_16x16x32_bf16 v[110:113], v[140:143], v[190:193], v[110:113]
	v_mfma_f32_16x16x32_bf16 v[106:109], v[152:155], v[190:193], v[106:109]
	v_mfma_f32_16x16x32_bf16 v[94:97], v[140:143], v[198:201], v[94:97]
	v_mfma_f32_16x16x32_bf16 v[90:93], v[152:155], v[198:201], v[90:93]
	v_mfma_f32_16x16x32_bf16 v[78:81], v[140:143], v[236:239], v[78:81]
	v_mfma_f32_16x16x32_bf16 v[74:77], v[152:155], v[236:239], v[74:77]
	v_mfma_f32_16x16x32_bf16 v[126:129], v[148:151], v[186:189], v[126:129]
	v_mfma_f32_16x16x32_bf16 v[122:125], v[156:159], v[186:189], v[122:125]
	v_mfma_f32_16x16x32_bf16 v[110:113], v[148:151], v[194:197], v[110:113]
	v_mfma_f32_16x16x32_bf16 v[106:109], v[156:159], v[194:197], v[106:109]
	v_mfma_f32_16x16x32_bf16 v[94:97], v[148:151], v[202:205], v[94:97]
	v_mfma_f32_16x16x32_bf16 v[90:93], v[156:159], v[202:205], v[90:93]
	v_mfma_f32_16x16x32_bf16 v[78:81], v[148:151], v[240:243], v[78:81]
	v_mfma_f32_16x16x32_bf16 v[74:77], v[156:159], v[240:243], v[74:77]
	v_mfma_f32_16x16x32_bf16 v[118:121], v[160:163], v[182:185], v[118:121]
	v_mfma_f32_16x16x32_bf16 v[114:117], v[174:177], v[182:185], v[114:117]
	v_mfma_f32_16x16x32_bf16 v[102:105], v[160:163], v[190:193], v[102:105]
	v_mfma_f32_16x16x32_bf16 v[98:101], v[174:177], v[190:193], v[98:101]
	v_mfma_f32_16x16x32_bf16 v[86:89], v[160:163], v[198:201], v[86:89]
	v_mfma_f32_16x16x32_bf16 v[82:85], v[174:177], v[198:201], v[82:85]
	v_mfma_f32_16x16x32_bf16 v[70:73], v[160:163], v[236:239], v[70:73]
	v_mfma_f32_16x16x32_bf16 v[66:69], v[174:177], v[236:239], v[66:69]
	v_mfma_f32_16x16x32_bf16 v[118:121], v[164:167], v[186:189], v[118:121]
	v_mfma_f32_16x16x32_bf16 v[114:117], v[178:181], v[186:189], v[114:117]
	v_mfma_f32_16x16x32_bf16 v[102:105], v[164:167], v[194:197], v[102:105]
	v_mfma_f32_16x16x32_bf16 v[98:101], v[178:181], v[194:197], v[98:101]
	v_mfma_f32_16x16x32_bf16 v[86:89], v[164:167], v[202:205], v[86:89]
	v_mfma_f32_16x16x32_bf16 v[82:85], v[178:181], v[202:205], v[82:85]
	v_mfma_f32_16x16x32_bf16 v[70:73], v[164:167], v[240:243], v[70:73]
	v_mfma_f32_16x16x32_bf16 v[66:69], v[178:181], v[240:243], v[66:69]
	s_barrier
	s_add_i32 s36, s36, s71
	v_lshl_add_u64 v[168:169], s[16:17], 0, v[0:1]
	s_mov_b32 m0, s36
	s_nop 0
	global_load_lds_dwordx4 v[168:169], off
	s_add_i32 m0, s36, 0x2000
	s_add_u32 s88, s16, 0x40000
	v_lshl_add_u64 v[206:207], s[16:17], 0, v[134:135]
	s_addc_u32 s89, s17, 0
	s_add_i32 s36, s37, s71
	global_load_lds_dwordx4 v[206:207], off
	v_lshl_add_u64 v[244:245], s[88:89], 0, v[0:1]
	s_mov_b32 m0, s36
	v_lshl_add_u64 v[246:247], s[18:19], 0, v[132:133]
	global_load_lds_dwordx4 v[244:245], off
	v_lshl_add_u64 v[244:245], s[88:89], 0, v[134:135]
	s_add_i32 m0, s36, 0x2000
	s_nop 0
	global_load_lds_dwordx4 v[244:245], off
	v_lshl_add_u64 v[244:245], s[18:19], 0, v[130:131]
	s_mov_b32 m0, s74
	s_nop 0
	global_load_lds_dwordx4 v[244:245], off
	s_mov_b32 m0, s75
	s_nop 0
	global_load_lds_dwordx4 v[246:247], off
	ds_read_b128 v[182:185], v147 offset:16384
	ds_read_b128 v[186:189], v147 offset:17408
	ds_read_b128 v[190:193], v147 offset:18432
	ds_read_b128 v[194:197], v147 offset:19456
	ds_read_b128 v[198:201], v147 offset:20480
	ds_read_b128 v[202:205], v147 offset:21504
	ds_read_b128 v[236:239], v147 offset:22528
	ds_read_b128 v[240:243], v147 offset:23552
	s_waitcnt vmcnt(8)
	s_waitcnt lgkmcnt(0)
	s_barrier
	s_waitcnt lgkmcnt(0)
	v_mfma_f32_16x16x32_bf16 v[62:65], v[140:143], v[182:185], v[62:65]
	v_mfma_f32_16x16x32_bf16 v[58:61], v[152:155], v[182:185], v[58:61]
	v_mfma_f32_16x16x32_bf16 v[46:49], v[140:143], v[190:193], v[46:49]
	v_mfma_f32_16x16x32_bf16 v[42:45], v[152:155], v[190:193], v[42:45]
	v_mfma_f32_16x16x32_bf16 v[30:33], v[140:143], v[198:201], v[30:33]
	v_mfma_f32_16x16x32_bf16 v[26:29], v[152:155], v[198:201], v[26:29]
	v_mfma_f32_16x16x32_bf16 v[14:17], v[140:143], v[236:239], v[14:17]
	v_mfma_f32_16x16x32_bf16 v[10:13], v[152:155], v[236:239], v[10:13]
	v_mfma_f32_16x16x32_bf16 v[62:65], v[148:151], v[186:189], v[62:65]
	v_mfma_f32_16x16x32_bf16 v[58:61], v[156:159], v[186:189], v[58:61]
	v_mfma_f32_16x16x32_bf16 v[46:49], v[148:151], v[194:197], v[46:49]
	v_mfma_f32_16x16x32_bf16 v[42:45], v[156:159], v[194:197], v[42:45]
	v_mfma_f32_16x16x32_bf16 v[30:33], v[148:151], v[202:205], v[30:33]
	v_mfma_f32_16x16x32_bf16 v[26:29], v[156:159], v[202:205], v[26:29]
	v_mfma_f32_16x16x32_bf16 v[14:17], v[148:151], v[240:243], v[14:17]
	v_mfma_f32_16x16x32_bf16 v[10:13], v[156:159], v[240:243], v[10:13]
	v_mfma_f32_16x16x32_bf16 v[54:57], v[160:163], v[182:185], v[54:57]
	v_mfma_f32_16x16x32_bf16 v[50:53], v[174:177], v[182:185], v[50:53]
	v_mfma_f32_16x16x32_bf16 v[38:41], v[160:163], v[190:193], v[38:41]
	v_mfma_f32_16x16x32_bf16 v[34:37], v[174:177], v[190:193], v[34:37]
	v_mfma_f32_16x16x32_bf16 v[22:25], v[160:163], v[198:201], v[22:25]
	v_mfma_f32_16x16x32_bf16 v[18:21], v[174:177], v[198:201], v[18:21]
	v_mfma_f32_16x16x32_bf16 v[6:9], v[160:163], v[236:239], v[6:9]
	v_mfma_f32_16x16x32_bf16 v[2:5], v[174:177], v[236:239], v[2:5]
	v_mfma_f32_16x16x32_bf16 v[54:57], v[164:167], v[186:189], v[54:57]
	v_mfma_f32_16x16x32_bf16 v[50:53], v[178:181], v[186:189], v[50:53]
	v_mfma_f32_16x16x32_bf16 v[38:41], v[164:167], v[194:197], v[38:41]
	v_mfma_f32_16x16x32_bf16 v[34:37], v[178:181], v[194:197], v[34:37]
	v_mfma_f32_16x16x32_bf16 v[22:25], v[164:167], v[202:205], v[22:25]
	v_mfma_f32_16x16x32_bf16 v[18:21], v[178:181], v[202:205], v[18:21]
	v_mfma_f32_16x16x32_bf16 v[6:9], v[164:167], v[240:243], v[6:9]
	v_mfma_f32_16x16x32_bf16 v[2:5], v[178:181], v[240:243], v[2:5]
	s_barrier
	s_add_i32 s36, 0, 0x18000
	s_add_i32 s37, 0, 0x1c000
	s_add_u32 s18, s18, 0x40000
	s_addc_u32 s19, s19, 0
	s_mov_b32 m0, s77
	v_lshl_add_u64 v[248:249], s[18:19], 0, v[130:131]
	global_load_lds_dwordx4 v[248:249], off
	v_lshl_add_u64 v[248:249], s[18:19], 0, v[132:133]
	s_mov_b32 m0, s78
	s_nop 0
	global_load_lds_dwordx4 v[248:249], off
	v_add_u32_e32 v156, s36, v145
	v_add_u32_e32 v178, s37, v145
	ds_read_b128 v[140:143], v156
	ds_read_b128 v[148:151], v156 offset:1024
	ds_read_b128 v[152:155], v156 offset:2048
	ds_read_b128 v[156:159], v156 offset:3072
	ds_read_b128 v[160:163], v178
	ds_read_b128 v[164:167], v178 offset:1024
	ds_read_b128 v[174:177], v178 offset:2048
	ds_read_b128 v[178:181], v178 offset:3072
	ds_read_b128 v[182:185], v147 offset:32768
	ds_read_b128 v[186:189], v147 offset:33792
	ds_read_b128 v[190:193], v147 offset:34816
	ds_read_b128 v[194:197], v147 offset:35840
	ds_read_b128 v[198:201], v147 offset:36864
	ds_read_b128 v[202:205], v147 offset:37888
	ds_read_b128 v[236:239], v147 offset:38912
	ds_read_b128 v[240:243], v147 offset:39936
	s_waitcnt vmcnt(8)
	s_waitcnt lgkmcnt(0)
	s_barrier
	s_waitcnt lgkmcnt(0)
	v_mfma_f32_16x16x32_bf16 v[126:129], v[140:143], v[182:185], v[126:129]
	v_mfma_f32_16x16x32_bf16 v[122:125], v[152:155], v[182:185], v[122:125]
	v_mfma_f32_16x16x32_bf16 v[110:113], v[140:143], v[190:193], v[110:113]
	v_mfma_f32_16x16x32_bf16 v[106:109], v[152:155], v[190:193], v[106:109]
	v_mfma_f32_16x16x32_bf16 v[94:97], v[140:143], v[198:201], v[94:97]
	v_mfma_f32_16x16x32_bf16 v[90:93], v[152:155], v[198:201], v[90:93]
	v_mfma_f32_16x16x32_bf16 v[78:81], v[140:143], v[236:239], v[78:81]
	v_mfma_f32_16x16x32_bf16 v[74:77], v[152:155], v[236:239], v[74:77]
	v_mfma_f32_16x16x32_bf16 v[126:129], v[148:151], v[186:189], v[126:129]
	v_mfma_f32_16x16x32_bf16 v[122:125], v[156:159], v[186:189], v[122:125]
	v_mfma_f32_16x16x32_bf16 v[110:113], v[148:151], v[194:197], v[110:113]
	v_mfma_f32_16x16x32_bf16 v[106:109], v[156:159], v[194:197], v[106:109]
	v_mfma_f32_16x16x32_bf16 v[94:97], v[148:151], v[202:205], v[94:97]
	v_mfma_f32_16x16x32_bf16 v[90:93], v[156:159], v[202:205], v[90:93]
	v_mfma_f32_16x16x32_bf16 v[78:81], v[148:151], v[240:243], v[78:81]
	v_mfma_f32_16x16x32_bf16 v[74:77], v[156:159], v[240:243], v[74:77]
	v_mfma_f32_16x16x32_bf16 v[118:121], v[160:163], v[182:185], v[118:121]
	v_mfma_f32_16x16x32_bf16 v[114:117], v[174:177], v[182:185], v[114:117]
	v_mfma_f32_16x16x32_bf16 v[102:105], v[160:163], v[190:193], v[102:105]
	v_mfma_f32_16x16x32_bf16 v[98:101], v[174:177], v[190:193], v[98:101]
	v_mfma_f32_16x16x32_bf16 v[86:89], v[160:163], v[198:201], v[86:89]
	v_mfma_f32_16x16x32_bf16 v[82:85], v[174:177], v[198:201], v[82:85]
	v_mfma_f32_16x16x32_bf16 v[70:73], v[160:163], v[236:239], v[70:73]
	v_mfma_f32_16x16x32_bf16 v[66:69], v[174:177], v[236:239], v[66:69]
	v_mfma_f32_16x16x32_bf16 v[118:121], v[164:167], v[186:189], v[118:121]
	v_mfma_f32_16x16x32_bf16 v[114:117], v[178:181], v[186:189], v[114:117]
	v_mfma_f32_16x16x32_bf16 v[102:105], v[164:167], v[194:197], v[102:105]
	v_mfma_f32_16x16x32_bf16 v[98:101], v[178:181], v[194:197], v[98:101]
	v_mfma_f32_16x16x32_bf16 v[86:89], v[164:167], v[202:205], v[86:89]
	v_mfma_f32_16x16x32_bf16 v[82:85], v[178:181], v[202:205], v[82:85]
	v_mfma_f32_16x16x32_bf16 v[70:73], v[164:167], v[240:243], v[70:73]
	v_mfma_f32_16x16x32_bf16 v[66:69], v[178:181], v[240:243], v[66:69]
	s_barrier
	s_add_i32 s18, s36, s71
	v_lshl_add_u64 v[168:169], v[168:169], 0, s[4:5]
	s_mov_b32 m0, s18
	s_nop 0
	global_load_lds_dwordx4 v[168:169], off
	s_add_i32 m0, s18, 0x2000
	s_add_u32 s16, s16, 0x40080
	v_lshl_add_u64 v[168:169], v[206:207], 0, s[4:5]
	s_addc_u32 s17, s17, 0
	s_add_i32 s18, s37, s71
	global_load_lds_dwordx4 v[168:169], off
	v_lshl_add_u64 v[168:169], s[16:17], 0, v[0:1]
	s_mov_b32 m0, s18
	s_nop 0
	global_load_lds_dwordx4 v[168:169], off
	v_lshl_add_u64 v[168:169], s[16:17], 0, v[134:135]
	s_add_i32 m0, s18, 0x2000
	s_nop 0
	global_load_lds_dwordx4 v[168:169], off
	v_lshl_add_u64 v[168:169], v[244:245], 0, s[4:5]
	s_mov_b32 m0, s79
	s_nop 0
	global_load_lds_dwordx4 v[168:169], off
	v_lshl_add_u64 v[168:169], v[246:247], 0, s[4:5]
	s_mov_b32 m0, s82
	s_nop 0
	global_load_lds_dwordx4 v[168:169], off
	ds_read_b128 v[182:185], v147 offset:49152
	ds_read_b128 v[186:189], v147 offset:50176
	ds_read_b128 v[190:193], v147 offset:51200
	ds_read_b128 v[194:197], v147 offset:52224
	ds_read_b128 v[198:201], v147 offset:53248
	ds_read_b128 v[202:205], v147 offset:54272
	ds_read_b128 v[236:239], v147 offset:55296
	ds_read_b128 v[240:243], v147 offset:56320
	s_waitcnt vmcnt(8)
	s_waitcnt lgkmcnt(0)
	s_barrier
	s_waitcnt lgkmcnt(0)
	v_mfma_f32_16x16x32_bf16 v[62:65], v[140:143], v[182:185], v[62:65]
	v_mfma_f32_16x16x32_bf16 v[58:61], v[152:155], v[182:185], v[58:61]
	v_mfma_f32_16x16x32_bf16 v[46:49], v[140:143], v[190:193], v[46:49]
	v_mfma_f32_16x16x32_bf16 v[42:45], v[152:155], v[190:193], v[42:45]
	v_mfma_f32_16x16x32_bf16 v[30:33], v[140:143], v[198:201], v[30:33]
	v_mfma_f32_16x16x32_bf16 v[26:29], v[152:155], v[198:201], v[26:29]
	v_mfma_f32_16x16x32_bf16 v[14:17], v[140:143], v[236:239], v[14:17]
	v_mfma_f32_16x16x32_bf16 v[10:13], v[152:155], v[236:239], v[10:13]
	v_mfma_f32_16x16x32_bf16 v[62:65], v[148:151], v[186:189], v[62:65]
	v_mfma_f32_16x16x32_bf16 v[58:61], v[156:159], v[186:189], v[58:61]
	v_mfma_f32_16x16x32_bf16 v[46:49], v[148:151], v[194:197], v[46:49]
	v_mfma_f32_16x16x32_bf16 v[42:45], v[156:159], v[194:197], v[42:45]
	v_mfma_f32_16x16x32_bf16 v[30:33], v[148:151], v[202:205], v[30:33]
	v_mfma_f32_16x16x32_bf16 v[26:29], v[156:159], v[202:205], v[26:29]
	v_mfma_f32_16x16x32_bf16 v[14:17], v[148:151], v[240:243], v[14:17]
	v_mfma_f32_16x16x32_bf16 v[10:13], v[156:159], v[240:243], v[10:13]
	v_mfma_f32_16x16x32_bf16 v[54:57], v[160:163], v[182:185], v[54:57]
	v_mfma_f32_16x16x32_bf16 v[50:53], v[174:177], v[182:185], v[50:53]
	v_mfma_f32_16x16x32_bf16 v[38:41], v[160:163], v[190:193], v[38:41]
	v_mfma_f32_16x16x32_bf16 v[34:37], v[174:177], v[190:193], v[34:37]
	v_mfma_f32_16x16x32_bf16 v[22:25], v[160:163], v[198:201], v[22:25]
	v_mfma_f32_16x16x32_bf16 v[18:21], v[174:177], v[198:201], v[18:21]
	v_mfma_f32_16x16x32_bf16 v[6:9], v[160:163], v[236:239], v[6:9]
	v_mfma_f32_16x16x32_bf16 v[2:5], v[174:177], v[236:239], v[2:5]
	v_mfma_f32_16x16x32_bf16 v[54:57], v[164:167], v[186:189], v[54:57]
	v_mfma_f32_16x16x32_bf16 v[50:53], v[178:181], v[186:189], v[50:53]
	v_mfma_f32_16x16x32_bf16 v[38:41], v[164:167], v[194:197], v[38:41]
	v_mfma_f32_16x16x32_bf16 v[34:37], v[178:181], v[194:197], v[34:37]
	v_mfma_f32_16x16x32_bf16 v[22:25], v[164:167], v[202:205], v[22:25]
	v_mfma_f32_16x16x32_bf16 v[18:21], v[178:181], v[202:205], v[18:21]
	v_mfma_f32_16x16x32_bf16 v[6:9], v[164:167], v[240:243], v[6:9]
	v_mfma_f32_16x16x32_bf16 v[2:5], v[178:181], v[240:243], v[2:5]
	s_barrier
	s_add_i32 s46, s46, 2
	s_add_u32 s14, s14, 0x100
	s_addc_u32 s15, s15, 0
	s_add_u32 s44, s44, 0x100
	s_addc_u32 s45, s45, 0
	s_cmp_gt_u32 s46, 13
	s_cbranch_scc0 .LBB0_493
	s_and_b64 vcc, exec, s[8:9]
	s_cbranch_vccz .LBB0_496
	s_barrier
